# EpiResid epilogue (D1/OUT/D2): the 32 serialized residual loads per wave hoisted and issued together, one vmcnt wait instead of 32
# baseline (speedup 1.0000x reference)
.LBB0_892:
	v_and_b32_e32 v138, 64, v208
	v_xor_b32_e32 v137, 16, v208
	v_add_u32_e32 v138, 64, v138
	v_cmp_lt_i32_e32 vcc, v137, v138
	v_lshl_add_u32 v136, s66, 8, v140
	v_lshl_or_b32 v134, s10, 8, v142
	v_cndmask_b32_e32 v137, v208, v137, vcc
	v_lshlrev_b32_e32 v144, 2, v137
	v_xor_b32_e32 v137, 32, v208
	v_cmp_lt_i32_e32 vcc, v137, v138
	v_ashrrev_i32_e32 v135, 31, v134
	s_lshl_b32 s30, s10, 2
	v_cndmask_b32_e32 v137, v208, v137, vcc
	v_lshlrev_b32_e32 v145, 2, v137
	v_ashrrev_i32_e32 v137, 31, v136
	v_lshlrev_b64 v[138:139], 11, v[136:137]
	v_lshl_add_u64 v[138:139], s[20:21], 0, v[138:139]
	v_lshl_add_u64 v[138:139], v[134:135], 1, v[138:139]
	global_load_dwordx2 v[166:167], v[138:139], off
	global_load_dwordx2 v[168:169], v[138:139], off offset:32
	global_load_dwordx2 v[170:171], v[138:139], off offset:256
	global_load_dwordx2 v[172:173], v[138:139], off offset:288
	v_add_co_u32_e32 v250, vcc, 0x8000, v138
	s_nop 1
	v_addc_co_u32_e32 v251, vcc, 0, v139, vcc
	global_load_dwordx2 v[174:175], v[250:251], off
	global_load_dwordx2 v[176:177], v[250:251], off offset:32
	global_load_dwordx2 v[178:179], v[250:251], off offset:256
	global_load_dwordx2 v[180:181], v[250:251], off offset:288
	v_add_co_u32_e32 v250, vcc, 0x10000, v138
	s_nop 1
	v_addc_co_u32_e32 v251, vcc, 0, v139, vcc
	global_load_dwordx2 v[182:183], v[250:251], off
	global_load_dwordx2 v[184:185], v[250:251], off offset:32
	global_load_dwordx2 v[186:187], v[250:251], off offset:256
	global_load_dwordx2 v[188:189], v[250:251], off offset:288
	v_add_co_u32_e32 v250, vcc, 0x18000, v138
	s_nop 1
	v_addc_co_u32_e32 v251, vcc, 0, v139, vcc
	global_load_dwordx2 v[190:191], v[250:251], off
	global_load_dwordx2 v[192:193], v[250:251], off offset:32
	global_load_dwordx2 v[194:195], v[250:251], off offset:256
	global_load_dwordx2 v[196:197], v[250:251], off offset:288
	v_add_co_u32_e32 v250, vcc, 0x40000, v138
	s_nop 1
	v_addc_co_u32_e32 v251, vcc, 0, v139, vcc
	global_load_dwordx2 v[198:199], v[250:251], off
	global_load_dwordx2 v[200:201], v[250:251], off offset:32
	global_load_dwordx2 v[202:203], v[250:251], off offset:256
	global_load_dwordx2 v[204:205], v[250:251], off offset:288
	v_add_co_u32_e32 v250, vcc, 0x48000, v138
	s_nop 1
	v_addc_co_u32_e32 v251, vcc, 0, v139, vcc
	global_load_dwordx2 v[206:207], v[250:251], off
	global_load_dwordx2 v[222:223], v[250:251], off offset:32
	global_load_dwordx2 v[224:225], v[250:251], off offset:256
	global_load_dwordx2 v[226:227], v[250:251], off offset:288
	v_add_co_u32_e32 v250, vcc, 0x50000, v138
	s_nop 1
	v_addc_co_u32_e32 v251, vcc, 0, v139, vcc
	global_load_dwordx2 v[228:229], v[250:251], off
	global_load_dwordx2 v[230:231], v[250:251], off offset:32
	global_load_dwordx2 v[232:233], v[250:251], off offset:256
	global_load_dwordx2 v[234:235], v[250:251], off offset:288
	v_add_co_u32_e32 v250, vcc, 0x58000, v138
	s_nop 1
	v_addc_co_u32_e32 v251, vcc, 0, v139, vcc
	global_load_dwordx2 v[236:237], v[250:251], off
	global_load_dwordx2 v[238:239], v[250:251], off offset:32
	global_load_dwordx2 v[240:241], v[250:251], off offset:256
	global_load_dwordx2 v[242:243], v[250:251], off offset:288
	s_waitcnt vmcnt(0)
	v_mov_b32_e32 v146, v166
	v_mov_b32_e32 v147, v167
	s_ashr_i32 s31, s30, 31
	v_lshlrev_b32_e32 v148, 16, v146
	v_and_b32_e32 v149, 0xffff0000, v146
	v_lshlrev_b32_e32 v146, 16, v147
	v_and_b32_e32 v147, 0xffff0000, v147
	v_pk_fma_f32 v[124:125], v[124:125], 0.5, v[148:149] op_sel_hi:[1,0,1]
	v_pk_fma_f32 v[126:127], v[126:127], 0.5, v[146:147] op_sel_hi:[1,0,1]
	v_cvt_pk_bf16_f32 v124, v124, v125
	v_cvt_pk_bf16_f32 v125, v126, v127
	global_store_dwordx2 v[138:139], v[124:125], off
	v_lshlrev_b32_e32 v126, 16, v124
	v_and_b32_e32 v124, 0xffff0000, v124
	v_lshlrev_b32_e32 v127, 16, v125
	v_and_b32_e32 v125, 0xffff0000, v125
	v_mul_f32_e32 v124, v124, v124
	v_mul_f32_e32 v125, v125, v125
	v_fmac_f32_e32 v124, v126, v126
	v_fmac_f32_e32 v125, v127, v127
	v_add_f32_e32 v146, v124, v125
	v_mov_b32_e32 v124, v168
	v_mov_b32_e32 v125, v169
	v_lshlrev_b32_e32 v126, 16, v124
	v_and_b32_e32 v127, 0xffff0000, v124
	v_lshlrev_b32_e32 v124, 16, v125
	v_and_b32_e32 v125, 0xffff0000, v125
	v_pk_fma_f32 v[120:121], v[120:121], 0.5, v[126:127] op_sel_hi:[1,0,1]
	v_pk_fma_f32 v[122:123], v[122:123], 0.5, v[124:125] op_sel_hi:[1,0,1]
	v_cvt_pk_bf16_f32 v120, v120, v121
	v_cvt_pk_bf16_f32 v121, v122, v123
	global_store_dwordx2 v[138:139], v[120:121], off offset:32
	v_lshlrev_b32_e32 v122, 16, v120
	v_and_b32_e32 v120, 0xffff0000, v120
	v_lshlrev_b32_e32 v123, 16, v121
	v_and_b32_e32 v121, 0xffff0000, v121
	v_mul_f32_e32 v120, v120, v120
	v_mul_f32_e32 v121, v121, v121
	v_fmac_f32_e32 v120, v122, v122
	v_fmac_f32_e32 v121, v123, v123
	v_add_f32_e32 v120, v120, v121
	v_add_f32_e32 v124, v146, v120
	v_mov_b32_e32 v120, v170
	v_mov_b32_e32 v121, v171
	v_lshlrev_b32_e32 v122, 16, v120
	v_and_b32_e32 v123, 0xffff0000, v120
	v_lshlrev_b32_e32 v120, 16, v121
	v_and_b32_e32 v121, 0xffff0000, v121
	v_pk_fma_f32 v[116:117], v[116:117], 0.5, v[122:123] op_sel_hi:[1,0,1]
	v_pk_fma_f32 v[118:119], v[118:119], 0.5, v[120:121] op_sel_hi:[1,0,1]
	v_cvt_pk_bf16_f32 v116, v116, v117
	v_cvt_pk_bf16_f32 v117, v118, v119
	global_store_dwordx2 v[138:139], v[116:117], off offset:256
	v_lshlrev_b32_e32 v118, 16, v116
	v_and_b32_e32 v116, 0xffff0000, v116
	v_lshlrev_b32_e32 v119, 16, v117
	v_and_b32_e32 v117, 0xffff0000, v117
	v_mul_f32_e32 v116, v116, v116
	v_mul_f32_e32 v117, v117, v117
	v_fmac_f32_e32 v116, v118, v118
	v_fmac_f32_e32 v117, v119, v119
	v_add_f32_e32 v116, v116, v117
	v_add_f32_e32 v120, v124, v116
	v_mov_b32_e32 v116, v172
	v_mov_b32_e32 v117, v173
	v_lshlrev_b32_e32 v118, 16, v116
	v_and_b32_e32 v119, 0xffff0000, v116
	v_lshlrev_b32_e32 v116, 16, v117
	v_and_b32_e32 v117, 0xffff0000, v117
	v_pk_fma_f32 v[112:113], v[112:113], 0.5, v[118:119] op_sel_hi:[1,0,1]
	v_pk_fma_f32 v[114:115], v[114:115], 0.5, v[116:117] op_sel_hi:[1,0,1]
	v_cvt_pk_bf16_f32 v112, v112, v113
	v_cvt_pk_bf16_f32 v113, v114, v115
	global_store_dwordx2 v[138:139], v[112:113], off offset:288
	v_lshlrev_b32_e32 v114, 16, v112
	v_and_b32_e32 v112, 0xffff0000, v112
	v_lshlrev_b32_e32 v115, 16, v113
	v_and_b32_e32 v113, 0xffff0000, v113
	v_mul_f32_e32 v112, v112, v112
	v_mul_f32_e32 v113, v113, v113
	v_fmac_f32_e32 v112, v114, v114
	v_fmac_f32_e32 v113, v115, v115
	v_add_f32_e32 v112, v112, v113
	v_add_f32_e32 v112, v120, v112
	ds_bpermute_b32 v113, v144, v112
	s_waitcnt lgkmcnt(0)
	v_add_f32_e32 v112, v112, v113
	ds_bpermute_b32 v113, v145, v112
	s_and_saveexec_b64 s[34:35], s[38:39]
	s_cbranch_execz .LBB0_894
	v_lshlrev_b64 v[114:115], 6, v[136:137]
	v_lshl_add_u64 v[114:115], s[22:23], 0, v[114:115]
	v_lshl_add_u64 v[114:115], s[30:31], 2, v[114:115]
	s_lshl_b32 s66, s58, 2
	v_lshl_add_u64 v[114:115], v[114:115], 0, s[66:67]
	s_waitcnt lgkmcnt(0)
	v_add_f32_e32 v112, v112, v113
	global_store_dword v[114:115], v112, off
.LBB0_894:
	s_or_b64 exec, exec, s[34:35]
	v_or_b32_e32 v112, 16, v136
	s_waitcnt lgkmcnt(0)
	v_ashrrev_i32_e32 v113, 31, v112
	v_lshlrev_b64 v[114:115], 11, v[112:113]
	v_lshl_add_u64 v[114:115], s[20:21], 0, v[114:115]
	v_lshl_add_u64 v[114:115], v[134:135], 1, v[114:115]
	v_mov_b32_e32 v116, v174
	v_mov_b32_e32 v117, v175
	v_lshlrev_b32_e32 v118, 16, v116
	v_and_b32_e32 v119, 0xffff0000, v116
	v_lshlrev_b32_e32 v116, 16, v117
	v_and_b32_e32 v117, 0xffff0000, v117
	v_pk_fma_f32 v[108:109], v[108:109], 0.5, v[118:119] op_sel_hi:[1,0,1]
	v_pk_fma_f32 v[110:111], v[110:111], 0.5, v[116:117] op_sel_hi:[1,0,1]
	v_cvt_pk_bf16_f32 v108, v108, v109
	v_cvt_pk_bf16_f32 v109, v110, v111
	global_store_dwordx2 v[114:115], v[108:109], off
	v_lshlrev_b32_e32 v110, 16, v108
	v_and_b32_e32 v108, 0xffff0000, v108
	v_lshlrev_b32_e32 v111, 16, v109
	v_and_b32_e32 v109, 0xffff0000, v109
	v_mul_f32_e32 v108, v108, v108
	v_mul_f32_e32 v109, v109, v109
	v_fmac_f32_e32 v108, v110, v110
	v_fmac_f32_e32 v109, v111, v111
	v_add_f32_e32 v116, v108, v109
	v_mov_b32_e32 v108, v176
	v_mov_b32_e32 v109, v177
	v_lshlrev_b32_e32 v110, 16, v108
	v_and_b32_e32 v111, 0xffff0000, v108
	v_lshlrev_b32_e32 v108, 16, v109
	v_and_b32_e32 v109, 0xffff0000, v109
	v_pk_fma_f32 v[104:105], v[104:105], 0.5, v[110:111] op_sel_hi:[1,0,1]
	v_pk_fma_f32 v[106:107], v[106:107], 0.5, v[108:109] op_sel_hi:[1,0,1]
	v_cvt_pk_bf16_f32 v104, v104, v105
	v_cvt_pk_bf16_f32 v105, v106, v107
	global_store_dwordx2 v[114:115], v[104:105], off offset:32
	v_lshlrev_b32_e32 v106, 16, v104
	v_and_b32_e32 v104, 0xffff0000, v104
	v_lshlrev_b32_e32 v107, 16, v105
	v_and_b32_e32 v105, 0xffff0000, v105
	v_mul_f32_e32 v104, v104, v104
	v_mul_f32_e32 v105, v105, v105
	v_fmac_f32_e32 v104, v106, v106
	v_fmac_f32_e32 v105, v107, v107
	v_add_f32_e32 v104, v104, v105
	v_add_f32_e32 v108, v116, v104
	v_mov_b32_e32 v104, v178
	v_mov_b32_e32 v105, v179
	v_lshlrev_b32_e32 v106, 16, v104
	v_and_b32_e32 v107, 0xffff0000, v104
	v_lshlrev_b32_e32 v104, 16, v105
	v_and_b32_e32 v105, 0xffff0000, v105
	v_pk_fma_f32 v[100:101], v[100:101], 0.5, v[106:107] op_sel_hi:[1,0,1]
	v_pk_fma_f32 v[102:103], v[102:103], 0.5, v[104:105] op_sel_hi:[1,0,1]
	v_cvt_pk_bf16_f32 v100, v100, v101
	v_cvt_pk_bf16_f32 v101, v102, v103
	global_store_dwordx2 v[114:115], v[100:101], off offset:256
	v_lshlrev_b32_e32 v102, 16, v100
	v_and_b32_e32 v100, 0xffff0000, v100
	v_lshlrev_b32_e32 v103, 16, v101
	v_and_b32_e32 v101, 0xffff0000, v101
	v_mul_f32_e32 v100, v100, v100
	v_mul_f32_e32 v101, v101, v101
	v_fmac_f32_e32 v100, v102, v102
	v_fmac_f32_e32 v101, v103, v103
	v_add_f32_e32 v100, v100, v101
	v_add_f32_e32 v104, v108, v100
	v_mov_b32_e32 v100, v180
	v_mov_b32_e32 v101, v181
	v_lshlrev_b32_e32 v102, 16, v100
	v_and_b32_e32 v103, 0xffff0000, v100
	v_lshlrev_b32_e32 v100, 16, v101
	v_and_b32_e32 v101, 0xffff0000, v101
	v_pk_fma_f32 v[96:97], v[96:97], 0.5, v[102:103] op_sel_hi:[1,0,1]
	v_pk_fma_f32 v[98:99], v[98:99], 0.5, v[100:101] op_sel_hi:[1,0,1]
	v_cvt_pk_bf16_f32 v96, v96, v97
	v_cvt_pk_bf16_f32 v97, v98, v99
	global_store_dwordx2 v[114:115], v[96:97], off offset:288
	v_lshlrev_b32_e32 v98, 16, v96
	v_and_b32_e32 v96, 0xffff0000, v96
	v_lshlrev_b32_e32 v99, 16, v97
	v_and_b32_e32 v97, 0xffff0000, v97
	v_mul_f32_e32 v96, v96, v96
	v_mul_f32_e32 v97, v97, v97
	v_fmac_f32_e32 v96, v98, v98
	v_fmac_f32_e32 v97, v99, v99
	v_add_f32_e32 v96, v96, v97
	v_add_f32_e32 v96, v104, v96
	ds_bpermute_b32 v97, v144, v96
	s_waitcnt lgkmcnt(0)
	v_add_f32_e32 v96, v96, v97
	ds_bpermute_b32 v97, v145, v96
	s_and_saveexec_b64 s[34:35], s[38:39]
	s_cbranch_execz .LBB0_896
	v_lshlrev_b64 v[98:99], 6, v[112:113]
	v_lshl_add_u64 v[98:99], s[22:23], 0, v[98:99]
	v_lshl_add_u64 v[98:99], s[30:31], 2, v[98:99]
	s_lshl_b32 s66, s58, 2
	v_lshl_add_u64 v[98:99], v[98:99], 0, s[66:67]
	s_waitcnt lgkmcnt(0)
	v_add_f32_e32 v96, v96, v97
	global_store_dword v[98:99], v96, off
.LBB0_896:
	s_or_b64 exec, exec, s[34:35]
	v_or_b32_e32 v96, 32, v136
	s_waitcnt lgkmcnt(0)
	v_ashrrev_i32_e32 v97, 31, v96
	v_lshlrev_b64 v[98:99], 11, v[96:97]
	v_lshl_add_u64 v[98:99], s[20:21], 0, v[98:99]
	v_lshl_add_u64 v[98:99], v[134:135], 1, v[98:99]
	v_mov_b32_e32 v100, v182
	v_mov_b32_e32 v101, v183
	v_lshlrev_b32_e32 v102, 16, v100
	v_and_b32_e32 v103, 0xffff0000, v100
	v_lshlrev_b32_e32 v100, 16, v101
	v_and_b32_e32 v101, 0xffff0000, v101
	v_pk_fma_f32 v[92:93], v[92:93], 0.5, v[102:103] op_sel_hi:[1,0,1]
	v_pk_fma_f32 v[94:95], v[94:95], 0.5, v[100:101] op_sel_hi:[1,0,1]
	v_cvt_pk_bf16_f32 v92, v92, v93
	v_cvt_pk_bf16_f32 v93, v94, v95
	global_store_dwordx2 v[98:99], v[92:93], off
	v_lshlrev_b32_e32 v94, 16, v92
	v_and_b32_e32 v92, 0xffff0000, v92
	v_lshlrev_b32_e32 v95, 16, v93
	v_and_b32_e32 v93, 0xffff0000, v93
	v_mul_f32_e32 v92, v92, v92
	v_mul_f32_e32 v93, v93, v93
	v_fmac_f32_e32 v92, v94, v94
	v_fmac_f32_e32 v93, v95, v95
	v_add_f32_e32 v100, v92, v93
	v_mov_b32_e32 v92, v184
	v_mov_b32_e32 v93, v185
	v_lshlrev_b32_e32 v94, 16, v92
	v_and_b32_e32 v95, 0xffff0000, v92
	v_lshlrev_b32_e32 v92, 16, v93
	v_and_b32_e32 v93, 0xffff0000, v93
	v_pk_fma_f32 v[88:89], v[88:89], 0.5, v[94:95] op_sel_hi:[1,0,1]
	v_pk_fma_f32 v[90:91], v[90:91], 0.5, v[92:93] op_sel_hi:[1,0,1]
	v_cvt_pk_bf16_f32 v88, v88, v89
	v_cvt_pk_bf16_f32 v89, v90, v91
	global_store_dwordx2 v[98:99], v[88:89], off offset:32
	v_lshlrev_b32_e32 v90, 16, v88
	v_and_b32_e32 v88, 0xffff0000, v88
	v_lshlrev_b32_e32 v91, 16, v89
	v_and_b32_e32 v89, 0xffff0000, v89
	v_mul_f32_e32 v88, v88, v88
	v_mul_f32_e32 v89, v89, v89
	v_fmac_f32_e32 v88, v90, v90
	v_fmac_f32_e32 v89, v91, v91
	v_add_f32_e32 v88, v88, v89
	v_add_f32_e32 v92, v100, v88
	v_mov_b32_e32 v88, v186
	v_mov_b32_e32 v89, v187
	v_lshlrev_b32_e32 v90, 16, v88
	v_and_b32_e32 v91, 0xffff0000, v88
	v_lshlrev_b32_e32 v88, 16, v89
	v_and_b32_e32 v89, 0xffff0000, v89
	v_pk_fma_f32 v[84:85], v[84:85], 0.5, v[90:91] op_sel_hi:[1,0,1]
	v_pk_fma_f32 v[86:87], v[86:87], 0.5, v[88:89] op_sel_hi:[1,0,1]
	v_cvt_pk_bf16_f32 v84, v84, v85
	v_cvt_pk_bf16_f32 v85, v86, v87
	global_store_dwordx2 v[98:99], v[84:85], off offset:256
	v_lshlrev_b32_e32 v86, 16, v84
	v_and_b32_e32 v84, 0xffff0000, v84
	v_lshlrev_b32_e32 v87, 16, v85
	v_and_b32_e32 v85, 0xffff0000, v85
	v_mul_f32_e32 v84, v84, v84
	v_mul_f32_e32 v85, v85, v85
	v_fmac_f32_e32 v84, v86, v86
	v_fmac_f32_e32 v85, v87, v87
	v_add_f32_e32 v84, v84, v85
	v_add_f32_e32 v88, v92, v84
	v_mov_b32_e32 v84, v188
	v_mov_b32_e32 v85, v189
	v_lshlrev_b32_e32 v86, 16, v84
	v_and_b32_e32 v87, 0xffff0000, v84
	v_lshlrev_b32_e32 v84, 16, v85
	v_and_b32_e32 v85, 0xffff0000, v85
	v_pk_fma_f32 v[80:81], v[80:81], 0.5, v[86:87] op_sel_hi:[1,0,1]
	v_pk_fma_f32 v[82:83], v[82:83], 0.5, v[84:85] op_sel_hi:[1,0,1]
	v_cvt_pk_bf16_f32 v80, v80, v81
	v_cvt_pk_bf16_f32 v81, v82, v83
	global_store_dwordx2 v[98:99], v[80:81], off offset:288
	v_lshlrev_b32_e32 v82, 16, v80
	v_and_b32_e32 v80, 0xffff0000, v80
	v_lshlrev_b32_e32 v83, 16, v81
	v_and_b32_e32 v81, 0xffff0000, v81
	v_mul_f32_e32 v80, v80, v80
	v_mul_f32_e32 v81, v81, v81
	v_fmac_f32_e32 v80, v82, v82
	v_fmac_f32_e32 v81, v83, v83
	v_add_f32_e32 v80, v80, v81
	v_add_f32_e32 v80, v88, v80
	ds_bpermute_b32 v81, v144, v80
	s_waitcnt lgkmcnt(0)
	v_add_f32_e32 v80, v80, v81
	ds_bpermute_b32 v81, v145, v80
	s_and_saveexec_b64 s[34:35], s[38:39]
	s_cbranch_execz .LBB0_898
	v_lshlrev_b64 v[82:83], 6, v[96:97]
	v_lshl_add_u64 v[82:83], s[22:23], 0, v[82:83]
	v_lshl_add_u64 v[82:83], s[30:31], 2, v[82:83]
	s_lshl_b32 s66, s58, 2
	v_lshl_add_u64 v[82:83], v[82:83], 0, s[66:67]
	s_waitcnt lgkmcnt(0)
	v_add_f32_e32 v80, v80, v81
	global_store_dword v[82:83], v80, off
.LBB0_898:
	s_or_b64 exec, exec, s[34:35]
	v_or_b32_e32 v80, 48, v136
	s_waitcnt lgkmcnt(0)
	v_ashrrev_i32_e32 v81, 31, v80
	v_lshlrev_b64 v[82:83], 11, v[80:81]
	v_lshl_add_u64 v[82:83], s[20:21], 0, v[82:83]
	v_lshl_add_u64 v[82:83], v[134:135], 1, v[82:83]
	v_mov_b32_e32 v84, v190
	v_mov_b32_e32 v85, v191
	v_lshlrev_b32_e32 v86, 16, v84
	v_and_b32_e32 v87, 0xffff0000, v84
	v_lshlrev_b32_e32 v84, 16, v85
	v_and_b32_e32 v85, 0xffff0000, v85
	v_pk_fma_f32 v[76:77], v[76:77], 0.5, v[86:87] op_sel_hi:[1,0,1]
	v_pk_fma_f32 v[78:79], v[78:79], 0.5, v[84:85] op_sel_hi:[1,0,1]
	v_cvt_pk_bf16_f32 v76, v76, v77
	v_cvt_pk_bf16_f32 v77, v78, v79
	global_store_dwordx2 v[82:83], v[76:77], off
	v_lshlrev_b32_e32 v78, 16, v76
	v_and_b32_e32 v76, 0xffff0000, v76
	v_lshlrev_b32_e32 v79, 16, v77
	v_and_b32_e32 v77, 0xffff0000, v77
	v_mul_f32_e32 v76, v76, v76
	v_mul_f32_e32 v77, v77, v77
	v_fmac_f32_e32 v76, v78, v78
	v_fmac_f32_e32 v77, v79, v79
	v_add_f32_e32 v84, v76, v77
	v_mov_b32_e32 v76, v192
	v_mov_b32_e32 v77, v193
	v_lshlrev_b32_e32 v78, 16, v76
	v_and_b32_e32 v79, 0xffff0000, v76
	v_lshlrev_b32_e32 v76, 16, v77
	v_and_b32_e32 v77, 0xffff0000, v77
	v_pk_fma_f32 v[72:73], v[72:73], 0.5, v[78:79] op_sel_hi:[1,0,1]
	v_pk_fma_f32 v[74:75], v[74:75], 0.5, v[76:77] op_sel_hi:[1,0,1]
	v_cvt_pk_bf16_f32 v72, v72, v73
	v_cvt_pk_bf16_f32 v73, v74, v75
	global_store_dwordx2 v[82:83], v[72:73], off offset:32
	v_lshlrev_b32_e32 v74, 16, v72
	v_and_b32_e32 v72, 0xffff0000, v72
	v_lshlrev_b32_e32 v75, 16, v73
	v_and_b32_e32 v73, 0xffff0000, v73
	v_mul_f32_e32 v72, v72, v72
	v_mul_f32_e32 v73, v73, v73
	v_fmac_f32_e32 v72, v74, v74
	v_fmac_f32_e32 v73, v75, v75
	v_add_f32_e32 v72, v72, v73
	v_add_f32_e32 v76, v84, v72
	v_mov_b32_e32 v72, v194
	v_mov_b32_e32 v73, v195
	v_lshlrev_b32_e32 v74, 16, v72
	v_and_b32_e32 v75, 0xffff0000, v72
	v_lshlrev_b32_e32 v72, 16, v73
	v_and_b32_e32 v73, 0xffff0000, v73
	v_pk_fma_f32 v[68:69], v[68:69], 0.5, v[74:75] op_sel_hi:[1,0,1]
	v_pk_fma_f32 v[70:71], v[70:71], 0.5, v[72:73] op_sel_hi:[1,0,1]
	v_cvt_pk_bf16_f32 v68, v68, v69
	v_cvt_pk_bf16_f32 v69, v70, v71
	global_store_dwordx2 v[82:83], v[68:69], off offset:256
	v_lshlrev_b32_e32 v70, 16, v68
	v_and_b32_e32 v68, 0xffff0000, v68
	v_lshlrev_b32_e32 v71, 16, v69
	v_and_b32_e32 v69, 0xffff0000, v69
	v_mul_f32_e32 v68, v68, v68
	v_mul_f32_e32 v69, v69, v69
	v_fmac_f32_e32 v68, v70, v70
	v_fmac_f32_e32 v69, v71, v71
	v_add_f32_e32 v68, v68, v69
	v_add_f32_e32 v72, v76, v68
	v_mov_b32_e32 v68, v196
	v_mov_b32_e32 v69, v197
	v_lshlrev_b32_e32 v70, 16, v68
	v_and_b32_e32 v71, 0xffff0000, v68
	v_lshlrev_b32_e32 v68, 16, v69
	v_and_b32_e32 v69, 0xffff0000, v69
	v_pk_fma_f32 v[64:65], v[64:65], 0.5, v[70:71] op_sel_hi:[1,0,1]
	v_pk_fma_f32 v[66:67], v[66:67], 0.5, v[68:69] op_sel_hi:[1,0,1]
	v_cvt_pk_bf16_f32 v64, v64, v65
	v_cvt_pk_bf16_f32 v65, v66, v67
	global_store_dwordx2 v[82:83], v[64:65], off offset:288
	v_lshlrev_b32_e32 v66, 16, v64
	v_and_b32_e32 v64, 0xffff0000, v64
	v_lshlrev_b32_e32 v67, 16, v65
	v_and_b32_e32 v65, 0xffff0000, v65
	v_mul_f32_e32 v64, v64, v64
	v_mul_f32_e32 v65, v65, v65
	v_fmac_f32_e32 v64, v66, v66
	v_fmac_f32_e32 v65, v67, v67
	v_add_f32_e32 v64, v64, v65
	v_add_f32_e32 v64, v72, v64
	ds_bpermute_b32 v65, v144, v64
	s_waitcnt lgkmcnt(0)
	v_add_f32_e32 v64, v64, v65
	ds_bpermute_b32 v65, v145, v64
	s_and_saveexec_b64 s[34:35], s[38:39]
	s_cbranch_execz .LBB0_900
	v_lshlrev_b64 v[66:67], 6, v[80:81]
	v_lshl_add_u64 v[66:67], s[22:23], 0, v[66:67]
	v_lshl_add_u64 v[66:67], s[30:31], 2, v[66:67]
	s_lshl_b32 s66, s58, 2
	v_lshl_add_u64 v[66:67], v[66:67], 0, s[66:67]
	s_waitcnt lgkmcnt(0)
	v_add_f32_e32 v64, v64, v65
	global_store_dword v[66:67], v64, off
.LBB0_900:
	s_or_b64 exec, exec, s[34:35]
	v_add_u32_e32 v64, 0x80, v136
	s_waitcnt lgkmcnt(0)
	v_ashrrev_i32_e32 v65, 31, v64
	v_lshlrev_b64 v[66:67], 11, v[64:65]
	v_lshl_add_u64 v[66:67], s[20:21], 0, v[66:67]
	v_lshl_add_u64 v[66:67], v[134:135], 1, v[66:67]
	v_mov_b32_e32 v68, v198
	v_mov_b32_e32 v69, v199
	v_lshlrev_b32_e32 v70, 16, v68
	v_and_b32_e32 v71, 0xffff0000, v68
	v_lshlrev_b32_e32 v68, 16, v69
	v_and_b32_e32 v69, 0xffff0000, v69
	v_pk_fma_f32 v[60:61], v[60:61], 0.5, v[70:71] op_sel_hi:[1,0,1]
	v_pk_fma_f32 v[62:63], v[62:63], 0.5, v[68:69] op_sel_hi:[1,0,1]
	v_cvt_pk_bf16_f32 v60, v60, v61
	v_cvt_pk_bf16_f32 v61, v62, v63
	global_store_dwordx2 v[66:67], v[60:61], off
	v_lshlrev_b32_e32 v62, 16, v60
	v_and_b32_e32 v60, 0xffff0000, v60
	v_lshlrev_b32_e32 v63, 16, v61
	v_and_b32_e32 v61, 0xffff0000, v61
	v_mul_f32_e32 v60, v60, v60
	v_mul_f32_e32 v61, v61, v61
	v_fmac_f32_e32 v60, v62, v62
	v_fmac_f32_e32 v61, v63, v63
	v_add_f32_e32 v68, v60, v61
	v_mov_b32_e32 v60, v200
	v_mov_b32_e32 v61, v201
	v_lshlrev_b32_e32 v62, 16, v60
	v_and_b32_e32 v63, 0xffff0000, v60
	v_lshlrev_b32_e32 v60, 16, v61
	v_and_b32_e32 v61, 0xffff0000, v61
	v_pk_fma_f32 v[56:57], v[56:57], 0.5, v[62:63] op_sel_hi:[1,0,1]
	v_pk_fma_f32 v[58:59], v[58:59], 0.5, v[60:61] op_sel_hi:[1,0,1]
	v_cvt_pk_bf16_f32 v56, v56, v57
	v_cvt_pk_bf16_f32 v57, v58, v59
	global_store_dwordx2 v[66:67], v[56:57], off offset:32
	v_lshlrev_b32_e32 v58, 16, v56
	v_and_b32_e32 v56, 0xffff0000, v56
	v_lshlrev_b32_e32 v59, 16, v57
	v_and_b32_e32 v57, 0xffff0000, v57
	v_mul_f32_e32 v56, v56, v56
	v_mul_f32_e32 v57, v57, v57
	v_fmac_f32_e32 v56, v58, v58
	v_fmac_f32_e32 v57, v59, v59
	v_add_f32_e32 v56, v56, v57
	v_add_f32_e32 v60, v68, v56
	v_mov_b32_e32 v56, v202
	v_mov_b32_e32 v57, v203
	v_lshlrev_b32_e32 v58, 16, v56
	v_and_b32_e32 v59, 0xffff0000, v56
	v_lshlrev_b32_e32 v56, 16, v57
	v_and_b32_e32 v57, 0xffff0000, v57
	v_pk_fma_f32 v[52:53], v[52:53], 0.5, v[58:59] op_sel_hi:[1,0,1]
	v_pk_fma_f32 v[54:55], v[54:55], 0.5, v[56:57] op_sel_hi:[1,0,1]
	v_cvt_pk_bf16_f32 v52, v52, v53
	v_cvt_pk_bf16_f32 v53, v54, v55
	global_store_dwordx2 v[66:67], v[52:53], off offset:256
	v_lshlrev_b32_e32 v54, 16, v52
	v_and_b32_e32 v52, 0xffff0000, v52
	v_lshlrev_b32_e32 v55, 16, v53
	v_and_b32_e32 v53, 0xffff0000, v53
	v_mul_f32_e32 v52, v52, v52
	v_mul_f32_e32 v53, v53, v53
	v_fmac_f32_e32 v52, v54, v54
	v_fmac_f32_e32 v53, v55, v55
	v_add_f32_e32 v52, v52, v53
	v_add_f32_e32 v56, v60, v52
	v_mov_b32_e32 v52, v204
	v_mov_b32_e32 v53, v205
	v_lshlrev_b32_e32 v54, 16, v52
	v_and_b32_e32 v55, 0xffff0000, v52
	v_lshlrev_b32_e32 v52, 16, v53
	v_and_b32_e32 v53, 0xffff0000, v53
	v_pk_fma_f32 v[48:49], v[48:49], 0.5, v[54:55] op_sel_hi:[1,0,1]
	v_pk_fma_f32 v[50:51], v[50:51], 0.5, v[52:53] op_sel_hi:[1,0,1]
	v_cvt_pk_bf16_f32 v48, v48, v49
	v_cvt_pk_bf16_f32 v49, v50, v51
	global_store_dwordx2 v[66:67], v[48:49], off offset:288
	v_lshlrev_b32_e32 v50, 16, v48
	v_and_b32_e32 v48, 0xffff0000, v48
	v_lshlrev_b32_e32 v51, 16, v49
	v_and_b32_e32 v49, 0xffff0000, v49
	v_mul_f32_e32 v48, v48, v48
	v_mul_f32_e32 v49, v49, v49
	v_fmac_f32_e32 v48, v50, v50
	v_fmac_f32_e32 v49, v51, v51
	v_add_f32_e32 v48, v48, v49
	v_add_f32_e32 v48, v56, v48
	ds_bpermute_b32 v49, v144, v48
	s_waitcnt lgkmcnt(0)
	v_add_f32_e32 v48, v48, v49
	ds_bpermute_b32 v49, v145, v48
	s_and_saveexec_b64 s[34:35], s[38:39]
	s_cbranch_execz .LBB0_902
	v_lshlrev_b64 v[50:51], 6, v[64:65]
	v_lshl_add_u64 v[50:51], s[22:23], 0, v[50:51]
	v_lshl_add_u64 v[50:51], s[30:31], 2, v[50:51]
	s_lshl_b32 s66, s58, 2
	v_lshl_add_u64 v[50:51], v[50:51], 0, s[66:67]
	s_waitcnt lgkmcnt(0)
	v_add_f32_e32 v48, v48, v49
	global_store_dword v[50:51], v48, off
.LBB0_902:
	s_or_b64 exec, exec, s[34:35]
	v_add_u32_e32 v48, 0x90, v136
	s_waitcnt lgkmcnt(0)
	v_ashrrev_i32_e32 v49, 31, v48
	v_lshlrev_b64 v[50:51], 11, v[48:49]
	v_lshl_add_u64 v[50:51], s[20:21], 0, v[50:51]
	v_lshl_add_u64 v[50:51], v[134:135], 1, v[50:51]
	v_mov_b32_e32 v52, v206
	v_mov_b32_e32 v53, v207
	v_lshlrev_b32_e32 v54, 16, v52
	v_and_b32_e32 v55, 0xffff0000, v52
	v_lshlrev_b32_e32 v52, 16, v53
	v_and_b32_e32 v53, 0xffff0000, v53
	v_pk_fma_f32 v[44:45], v[44:45], 0.5, v[54:55] op_sel_hi:[1,0,1]
	v_pk_fma_f32 v[46:47], v[46:47], 0.5, v[52:53] op_sel_hi:[1,0,1]
	v_cvt_pk_bf16_f32 v44, v44, v45
	v_cvt_pk_bf16_f32 v45, v46, v47
	global_store_dwordx2 v[50:51], v[44:45], off
	v_lshlrev_b32_e32 v46, 16, v44
	v_and_b32_e32 v44, 0xffff0000, v44
	v_lshlrev_b32_e32 v47, 16, v45
	v_and_b32_e32 v45, 0xffff0000, v45
	v_mul_f32_e32 v44, v44, v44
	v_mul_f32_e32 v45, v45, v45
	v_fmac_f32_e32 v44, v46, v46
	v_fmac_f32_e32 v45, v47, v47
	v_add_f32_e32 v52, v44, v45
	v_mov_b32_e32 v44, v222
	v_mov_b32_e32 v45, v223
	v_lshlrev_b32_e32 v46, 16, v44
	v_and_b32_e32 v47, 0xffff0000, v44
	v_lshlrev_b32_e32 v44, 16, v45
	v_and_b32_e32 v45, 0xffff0000, v45
	v_pk_fma_f32 v[40:41], v[40:41], 0.5, v[46:47] op_sel_hi:[1,0,1]
	v_pk_fma_f32 v[42:43], v[42:43], 0.5, v[44:45] op_sel_hi:[1,0,1]
	v_cvt_pk_bf16_f32 v40, v40, v41
	v_cvt_pk_bf16_f32 v41, v42, v43
	global_store_dwordx2 v[50:51], v[40:41], off offset:32
	v_lshlrev_b32_e32 v42, 16, v40
	v_and_b32_e32 v40, 0xffff0000, v40
	v_lshlrev_b32_e32 v43, 16, v41
	v_and_b32_e32 v41, 0xffff0000, v41
	v_mul_f32_e32 v40, v40, v40
	v_mul_f32_e32 v41, v41, v41
	v_fmac_f32_e32 v40, v42, v42
	v_fmac_f32_e32 v41, v43, v43
	v_add_f32_e32 v40, v40, v41
	v_add_f32_e32 v44, v52, v40
	v_mov_b32_e32 v40, v224
	v_mov_b32_e32 v41, v225
	v_lshlrev_b32_e32 v42, 16, v40
	v_and_b32_e32 v43, 0xffff0000, v40
	v_lshlrev_b32_e32 v40, 16, v41
	v_and_b32_e32 v41, 0xffff0000, v41
	v_pk_fma_f32 v[36:37], v[36:37], 0.5, v[42:43] op_sel_hi:[1,0,1]
	v_pk_fma_f32 v[38:39], v[38:39], 0.5, v[40:41] op_sel_hi:[1,0,1]
	v_cvt_pk_bf16_f32 v36, v36, v37
	v_cvt_pk_bf16_f32 v37, v38, v39
	global_store_dwordx2 v[50:51], v[36:37], off offset:256
	v_lshlrev_b32_e32 v38, 16, v36
	v_and_b32_e32 v36, 0xffff0000, v36
	v_lshlrev_b32_e32 v39, 16, v37
	v_and_b32_e32 v37, 0xffff0000, v37
	v_mul_f32_e32 v36, v36, v36
	v_mul_f32_e32 v37, v37, v37
	v_fmac_f32_e32 v36, v38, v38
	v_fmac_f32_e32 v37, v39, v39
	v_add_f32_e32 v36, v36, v37
	v_add_f32_e32 v40, v44, v36
	v_mov_b32_e32 v36, v226
	v_mov_b32_e32 v37, v227
	v_lshlrev_b32_e32 v38, 16, v36
	v_and_b32_e32 v39, 0xffff0000, v36
	v_lshlrev_b32_e32 v36, 16, v37
	v_and_b32_e32 v37, 0xffff0000, v37
	v_pk_fma_f32 v[32:33], v[32:33], 0.5, v[38:39] op_sel_hi:[1,0,1]
	v_pk_fma_f32 v[34:35], v[34:35], 0.5, v[36:37] op_sel_hi:[1,0,1]
	v_cvt_pk_bf16_f32 v32, v32, v33
	v_cvt_pk_bf16_f32 v33, v34, v35
	global_store_dwordx2 v[50:51], v[32:33], off offset:288
	v_lshlrev_b32_e32 v34, 16, v32
	v_and_b32_e32 v32, 0xffff0000, v32
	v_lshlrev_b32_e32 v35, 16, v33
	v_and_b32_e32 v33, 0xffff0000, v33
	v_mul_f32_e32 v32, v32, v32
	v_mul_f32_e32 v33, v33, v33
	v_fmac_f32_e32 v32, v34, v34
	v_fmac_f32_e32 v33, v35, v35
	v_add_f32_e32 v32, v32, v33
	v_add_f32_e32 v32, v40, v32
	ds_bpermute_b32 v33, v144, v32
	s_waitcnt lgkmcnt(0)
	v_add_f32_e32 v32, v32, v33
	ds_bpermute_b32 v33, v145, v32
	s_and_saveexec_b64 s[34:35], s[38:39]
	s_cbranch_execz .LBB0_904
	v_lshlrev_b64 v[34:35], 6, v[48:49]
	v_lshl_add_u64 v[34:35], s[22:23], 0, v[34:35]
	v_lshl_add_u64 v[34:35], s[30:31], 2, v[34:35]
	s_lshl_b32 s66, s58, 2
	v_lshl_add_u64 v[34:35], v[34:35], 0, s[66:67]
	s_waitcnt lgkmcnt(0)
	v_add_f32_e32 v32, v32, v33
	global_store_dword v[34:35], v32, off
.LBB0_904:
	s_or_b64 exec, exec, s[34:35]
	v_add_u32_e32 v32, 0xa0, v136
	s_waitcnt lgkmcnt(0)
	v_ashrrev_i32_e32 v33, 31, v32
	v_lshlrev_b64 v[34:35], 11, v[32:33]
	v_lshl_add_u64 v[34:35], s[20:21], 0, v[34:35]
	v_lshl_add_u64 v[34:35], v[134:135], 1, v[34:35]
	v_mov_b32_e32 v36, v228
	v_mov_b32_e32 v37, v229
	v_lshlrev_b32_e32 v38, 16, v36
	v_and_b32_e32 v39, 0xffff0000, v36
	v_lshlrev_b32_e32 v36, 16, v37
	v_and_b32_e32 v37, 0xffff0000, v37
	v_pk_fma_f32 v[28:29], v[28:29], 0.5, v[38:39] op_sel_hi:[1,0,1]
	v_pk_fma_f32 v[30:31], v[30:31], 0.5, v[36:37] op_sel_hi:[1,0,1]
	v_cvt_pk_bf16_f32 v28, v28, v29
	v_cvt_pk_bf16_f32 v29, v30, v31
	global_store_dwordx2 v[34:35], v[28:29], off
	v_lshlrev_b32_e32 v30, 16, v28
	v_and_b32_e32 v28, 0xffff0000, v28
	v_lshlrev_b32_e32 v31, 16, v29
	v_and_b32_e32 v29, 0xffff0000, v29
	v_mul_f32_e32 v28, v28, v28
	v_mul_f32_e32 v29, v29, v29
	v_fmac_f32_e32 v28, v30, v30
	v_fmac_f32_e32 v29, v31, v31
	v_add_f32_e32 v36, v28, v29
	v_mov_b32_e32 v28, v230
	v_mov_b32_e32 v29, v231
	v_lshlrev_b32_e32 v30, 16, v28
	v_and_b32_e32 v31, 0xffff0000, v28
	v_lshlrev_b32_e32 v28, 16, v29
	v_and_b32_e32 v29, 0xffff0000, v29
	v_pk_fma_f32 v[24:25], v[24:25], 0.5, v[30:31] op_sel_hi:[1,0,1]
	v_pk_fma_f32 v[26:27], v[26:27], 0.5, v[28:29] op_sel_hi:[1,0,1]
	v_cvt_pk_bf16_f32 v24, v24, v25
	v_cvt_pk_bf16_f32 v25, v26, v27
	global_store_dwordx2 v[34:35], v[24:25], off offset:32
	v_lshlrev_b32_e32 v26, 16, v24
	v_and_b32_e32 v24, 0xffff0000, v24
	v_lshlrev_b32_e32 v27, 16, v25
	v_and_b32_e32 v25, 0xffff0000, v25
	v_mul_f32_e32 v24, v24, v24
	v_mul_f32_e32 v25, v25, v25
	v_fmac_f32_e32 v24, v26, v26
	v_fmac_f32_e32 v25, v27, v27
	v_add_f32_e32 v24, v24, v25
	v_add_f32_e32 v28, v36, v24
	v_mov_b32_e32 v24, v232
	v_mov_b32_e32 v25, v233
	v_lshlrev_b32_e32 v26, 16, v24
	v_and_b32_e32 v27, 0xffff0000, v24
	v_lshlrev_b32_e32 v24, 16, v25
	v_and_b32_e32 v25, 0xffff0000, v25
	v_pk_fma_f32 v[20:21], v[20:21], 0.5, v[26:27] op_sel_hi:[1,0,1]
	v_pk_fma_f32 v[22:23], v[22:23], 0.5, v[24:25] op_sel_hi:[1,0,1]
	v_cvt_pk_bf16_f32 v20, v20, v21
	v_cvt_pk_bf16_f32 v21, v22, v23
	global_store_dwordx2 v[34:35], v[20:21], off offset:256
	v_lshlrev_b32_e32 v22, 16, v20
	v_and_b32_e32 v20, 0xffff0000, v20
	v_lshlrev_b32_e32 v23, 16, v21
	v_and_b32_e32 v21, 0xffff0000, v21
	v_mul_f32_e32 v20, v20, v20
	v_mul_f32_e32 v21, v21, v21
	v_fmac_f32_e32 v20, v22, v22
	v_fmac_f32_e32 v21, v23, v23
	v_add_f32_e32 v20, v20, v21
	v_add_f32_e32 v24, v28, v20
	v_mov_b32_e32 v20, v234
	v_mov_b32_e32 v21, v235
	v_lshlrev_b32_e32 v22, 16, v20
	v_and_b32_e32 v23, 0xffff0000, v20
	v_lshlrev_b32_e32 v20, 16, v21
	v_and_b32_e32 v21, 0xffff0000, v21
	v_pk_fma_f32 v[16:17], v[16:17], 0.5, v[22:23] op_sel_hi:[1,0,1]
	v_pk_fma_f32 v[18:19], v[18:19], 0.5, v[20:21] op_sel_hi:[1,0,1]
	v_cvt_pk_bf16_f32 v16, v16, v17
	v_cvt_pk_bf16_f32 v17, v18, v19
	global_store_dwordx2 v[34:35], v[16:17], off offset:288
	v_lshlrev_b32_e32 v18, 16, v16
	v_and_b32_e32 v16, 0xffff0000, v16
	v_lshlrev_b32_e32 v19, 16, v17
	v_and_b32_e32 v17, 0xffff0000, v17
	v_mul_f32_e32 v16, v16, v16
	v_mul_f32_e32 v17, v17, v17
	v_fmac_f32_e32 v16, v18, v18
	v_fmac_f32_e32 v17, v19, v19
	v_add_f32_e32 v16, v16, v17
	v_add_f32_e32 v16, v24, v16
	ds_bpermute_b32 v17, v144, v16
	s_waitcnt lgkmcnt(0)
	v_add_f32_e32 v16, v16, v17
	ds_bpermute_b32 v17, v145, v16
	s_and_saveexec_b64 s[34:35], s[38:39]
	s_cbranch_execz .LBB0_906
	v_lshlrev_b64 v[18:19], 6, v[32:33]
	v_lshl_add_u64 v[18:19], s[22:23], 0, v[18:19]
	v_lshl_add_u64 v[18:19], s[30:31], 2, v[18:19]
	s_lshl_b32 s66, s58, 2
	v_lshl_add_u64 v[18:19], v[18:19], 0, s[66:67]
	s_waitcnt lgkmcnt(0)
	v_add_f32_e32 v16, v16, v17
	global_store_dword v[18:19], v16, off
.LBB0_906:
	s_or_b64 exec, exec, s[34:35]
	v_add_u32_e32 v16, 0xb0, v136
	s_waitcnt lgkmcnt(0)
	v_ashrrev_i32_e32 v17, 31, v16
	v_lshlrev_b64 v[18:19], 11, v[16:17]
	v_lshl_add_u64 v[18:19], s[20:21], 0, v[18:19]
	v_lshl_add_u64 v[18:19], v[134:135], 1, v[18:19]
	v_mov_b32_e32 v20, v236
	v_mov_b32_e32 v21, v237
	v_lshlrev_b32_e32 v22, 16, v20
	v_and_b32_e32 v23, 0xffff0000, v20
	v_lshlrev_b32_e32 v20, 16, v21
	v_and_b32_e32 v21, 0xffff0000, v21
	v_pk_fma_f32 v[12:13], v[12:13], 0.5, v[22:23] op_sel_hi:[1,0,1]
	v_pk_fma_f32 v[14:15], v[14:15], 0.5, v[20:21] op_sel_hi:[1,0,1]
	v_cvt_pk_bf16_f32 v12, v12, v13
	v_cvt_pk_bf16_f32 v13, v14, v15
	global_store_dwordx2 v[18:19], v[12:13], off
	v_lshlrev_b32_e32 v14, 16, v12
	v_and_b32_e32 v12, 0xffff0000, v12
	v_lshlrev_b32_e32 v15, 16, v13
	v_and_b32_e32 v13, 0xffff0000, v13
	v_mul_f32_e32 v12, v12, v12
	v_mul_f32_e32 v13, v13, v13
	v_fmac_f32_e32 v12, v14, v14
	v_fmac_f32_e32 v13, v15, v15
	v_add_f32_e32 v20, v12, v13
	v_mov_b32_e32 v12, v238
	v_mov_b32_e32 v13, v239
	v_lshlrev_b32_e32 v14, 16, v12
	v_and_b32_e32 v15, 0xffff0000, v12
	v_lshlrev_b32_e32 v12, 16, v13
	v_and_b32_e32 v13, 0xffff0000, v13
	v_pk_fma_f32 v[8:9], v[8:9], 0.5, v[14:15] op_sel_hi:[1,0,1]
	v_pk_fma_f32 v[10:11], v[10:11], 0.5, v[12:13] op_sel_hi:[1,0,1]
	v_cvt_pk_bf16_f32 v8, v8, v9
	v_cvt_pk_bf16_f32 v9, v10, v11
	global_store_dwordx2 v[18:19], v[8:9], off offset:32
	v_lshlrev_b32_e32 v10, 16, v8
	v_and_b32_e32 v8, 0xffff0000, v8
	v_lshlrev_b32_e32 v11, 16, v9
	v_and_b32_e32 v9, 0xffff0000, v9
	v_mul_f32_e32 v8, v8, v8
	v_mul_f32_e32 v9, v9, v9
	v_fmac_f32_e32 v8, v10, v10
	v_fmac_f32_e32 v9, v11, v11
	v_add_f32_e32 v8, v8, v9
	v_add_f32_e32 v12, v20, v8
	v_mov_b32_e32 v8, v240
	v_mov_b32_e32 v9, v241
	v_lshlrev_b32_e32 v10, 16, v8
	v_and_b32_e32 v11, 0xffff0000, v8
	v_lshlrev_b32_e32 v8, 16, v9
	v_and_b32_e32 v9, 0xffff0000, v9
	v_pk_fma_f32 v[4:5], v[4:5], 0.5, v[10:11] op_sel_hi:[1,0,1]
	v_pk_fma_f32 v[6:7], v[6:7], 0.5, v[8:9] op_sel_hi:[1,0,1]
	v_cvt_pk_bf16_f32 v4, v4, v5
	v_cvt_pk_bf16_f32 v5, v6, v7
	global_store_dwordx2 v[18:19], v[4:5], off offset:256
	v_lshlrev_b32_e32 v6, 16, v4
	v_and_b32_e32 v4, 0xffff0000, v4
	v_lshlrev_b32_e32 v7, 16, v5
	v_and_b32_e32 v5, 0xffff0000, v5
	v_mul_f32_e32 v4, v4, v4
	v_mul_f32_e32 v5, v5, v5
	v_fmac_f32_e32 v4, v6, v6
	v_fmac_f32_e32 v5, v7, v7
	v_add_f32_e32 v4, v4, v5
	v_add_f32_e32 v8, v12, v4
	v_mov_b32_e32 v4, v242
	v_mov_b32_e32 v5, v243
	v_lshlrev_b32_e32 v6, 16, v4
	v_and_b32_e32 v7, 0xffff0000, v4
	v_lshlrev_b32_e32 v4, 16, v5
	v_and_b32_e32 v5, 0xffff0000, v5
	v_pk_fma_f32 v[0:1], v[0:1], 0.5, v[6:7] op_sel_hi:[1,0,1]
	v_pk_fma_f32 v[2:3], v[2:3], 0.5, v[4:5] op_sel_hi:[1,0,1]
	v_cvt_pk_bf16_f32 v0, v0, v1
	v_cvt_pk_bf16_f32 v1, v2, v3
	global_store_dwordx2 v[18:19], v[0:1], off offset:288
	v_lshlrev_b32_e32 v2, 16, v0
	v_and_b32_e32 v0, 0xffff0000, v0
	v_lshlrev_b32_e32 v3, 16, v1
	v_and_b32_e32 v1, 0xffff0000, v1
	v_mul_f32_e32 v0, v0, v0
	v_mul_f32_e32 v1, v1, v1
	v_fmac_f32_e32 v0, v2, v2
	v_fmac_f32_e32 v1, v3, v3
	v_add_f32_e32 v0, v0, v1
	v_add_f32_e32 v0, v8, v0
	ds_bpermute_b32 v1, v144, v0
	s_waitcnt lgkmcnt(0)
	v_add_f32_e32 v0, v0, v1
	ds_bpermute_b32 v1, v145, v0
	s_and_saveexec_b64 s[34:35], s[38:39]
	s_cbranch_execz .LBB0_908
	v_lshlrev_b64 v[2:3], 6, v[16:17]
	v_lshl_add_u64 v[2:3], s[22:23], 0, v[2:3]
	v_lshl_add_u64 v[2:3], s[30:31], 2, v[2:3]
	s_lshl_b32 s66, s58, 2
	v_lshl_add_u64 v[2:3], v[2:3], 0, s[66:67]
	s_waitcnt lgkmcnt(0)
	v_add_f32_e32 v0, v0, v1
	global_store_dword v[2:3], v0, off

.LBB0_1990:
	v_and_b32_e32 v138, 64, v208
	v_xor_b32_e32 v137, 16, v208
	v_add_u32_e32 v138, 64, v138
	v_cmp_lt_i32_e32 vcc, v137, v138
	v_lshl_add_u32 v136, s66, 8, v140
	v_lshl_or_b32 v134, s10, 8, v142
	v_cndmask_b32_e32 v137, v208, v137, vcc
	v_lshlrev_b32_e32 v144, 2, v137
	v_xor_b32_e32 v137, 32, v208
	v_cmp_lt_i32_e32 vcc, v137, v138
	v_ashrrev_i32_e32 v135, 31, v134
	s_lshl_b32 s30, s10, 2
	v_cndmask_b32_e32 v137, v208, v137, vcc
	v_lshlrev_b32_e32 v145, 2, v137
	v_ashrrev_i32_e32 v137, 31, v136
	v_lshlrev_b64 v[138:139], 11, v[136:137]
	v_lshl_add_u64 v[138:139], s[20:21], 0, v[138:139]
	v_lshl_add_u64 v[138:139], v[134:135], 1, v[138:139]
	global_load_dwordx2 v[166:167], v[138:139], off
	global_load_dwordx2 v[168:169], v[138:139], off offset:32
	global_load_dwordx2 v[170:171], v[138:139], off offset:256
	global_load_dwordx2 v[172:173], v[138:139], off offset:288
	v_add_co_u32_e32 v250, vcc, 0x8000, v138
	s_nop 1
	v_addc_co_u32_e32 v251, vcc, 0, v139, vcc
	global_load_dwordx2 v[174:175], v[250:251], off
	global_load_dwordx2 v[176:177], v[250:251], off offset:32
	global_load_dwordx2 v[178:179], v[250:251], off offset:256
	global_load_dwordx2 v[180:181], v[250:251], off offset:288
	v_add_co_u32_e32 v250, vcc, 0x10000, v138
	s_nop 1
	v_addc_co_u32_e32 v251, vcc, 0, v139, vcc
	global_load_dwordx2 v[182:183], v[250:251], off
	global_load_dwordx2 v[184:185], v[250:251], off offset:32
	global_load_dwordx2 v[186:187], v[250:251], off offset:256
	global_load_dwordx2 v[188:189], v[250:251], off offset:288
	v_add_co_u32_e32 v250, vcc, 0x18000, v138
	s_nop 1
	v_addc_co_u32_e32 v251, vcc, 0, v139, vcc
	global_load_dwordx2 v[190:191], v[250:251], off
	global_load_dwordx2 v[192:193], v[250:251], off offset:32
	global_load_dwordx2 v[194:195], v[250:251], off offset:256
	global_load_dwordx2 v[196:197], v[250:251], off offset:288
	v_add_co_u32_e32 v250, vcc, 0x40000, v138
	s_nop 1
	v_addc_co_u32_e32 v251, vcc, 0, v139, vcc
	global_load_dwordx2 v[198:199], v[250:251], off
	global_load_dwordx2 v[200:201], v[250:251], off offset:32
	global_load_dwordx2 v[202:203], v[250:251], off offset:256
	global_load_dwordx2 v[204:205], v[250:251], off offset:288
	v_add_co_u32_e32 v250, vcc, 0x48000, v138
	s_nop 1
	v_addc_co_u32_e32 v251, vcc, 0, v139, vcc
	global_load_dwordx2 v[206:207], v[250:251], off
	global_load_dwordx2 v[222:223], v[250:251], off offset:32
	global_load_dwordx2 v[224:225], v[250:251], off offset:256
	global_load_dwordx2 v[226:227], v[250:251], off offset:288
	v_add_co_u32_e32 v250, vcc, 0x50000, v138
	s_nop 1
	v_addc_co_u32_e32 v251, vcc, 0, v139, vcc
	global_load_dwordx2 v[228:229], v[250:251], off
	global_load_dwordx2 v[230:231], v[250:251], off offset:32
	global_load_dwordx2 v[232:233], v[250:251], off offset:256
	global_load_dwordx2 v[234:235], v[250:251], off offset:288
	v_add_co_u32_e32 v250, vcc, 0x58000, v138
	s_nop 1
	v_addc_co_u32_e32 v251, vcc, 0, v139, vcc
	global_load_dwordx2 v[236:237], v[250:251], off
	global_load_dwordx2 v[238:239], v[250:251], off offset:32
	global_load_dwordx2 v[240:241], v[250:251], off offset:256
	global_load_dwordx2 v[242:243], v[250:251], off offset:288
	s_waitcnt vmcnt(0)
	v_mov_b32_e32 v146, v166
	v_mov_b32_e32 v147, v167
	s_ashr_i32 s31, s30, 31
	v_lshlrev_b32_e32 v148, 16, v146
	v_and_b32_e32 v149, 0xffff0000, v146
	v_lshlrev_b32_e32 v146, 16, v147
	v_and_b32_e32 v147, 0xffff0000, v147
	v_pk_add_f32 v[124:125], v[124:125], v[148:149]
	v_pk_add_f32 v[126:127], v[126:127], v[146:147]
	v_cvt_pk_bf16_f32 v124, v124, v125
	v_cvt_pk_bf16_f32 v125, v126, v127
	global_store_dwordx2 v[138:139], v[124:125], off
	v_lshlrev_b32_e32 v126, 16, v124
	v_and_b32_e32 v124, 0xffff0000, v124
	v_lshlrev_b32_e32 v127, 16, v125
	v_and_b32_e32 v125, 0xffff0000, v125
	v_mul_f32_e32 v124, v124, v124
	v_mul_f32_e32 v125, v125, v125
	v_fmac_f32_e32 v124, v126, v126
	v_fmac_f32_e32 v125, v127, v127
	v_add_f32_e32 v146, v124, v125
	v_mov_b32_e32 v124, v168
	v_mov_b32_e32 v125, v169
	v_lshlrev_b32_e32 v126, 16, v124
	v_and_b32_e32 v127, 0xffff0000, v124
	v_lshlrev_b32_e32 v124, 16, v125
	v_and_b32_e32 v125, 0xffff0000, v125
	v_pk_add_f32 v[120:121], v[120:121], v[126:127]
	v_pk_add_f32 v[122:123], v[122:123], v[124:125]
	v_cvt_pk_bf16_f32 v120, v120, v121
	v_cvt_pk_bf16_f32 v121, v122, v123
	global_store_dwordx2 v[138:139], v[120:121], off offset:32
	v_lshlrev_b32_e32 v122, 16, v120
	v_and_b32_e32 v120, 0xffff0000, v120
	v_lshlrev_b32_e32 v123, 16, v121
	v_and_b32_e32 v121, 0xffff0000, v121
	v_mul_f32_e32 v120, v120, v120
	v_mul_f32_e32 v121, v121, v121
	v_fmac_f32_e32 v120, v122, v122
	v_fmac_f32_e32 v121, v123, v123
	v_add_f32_e32 v120, v120, v121
	v_add_f32_e32 v124, v146, v120
	v_mov_b32_e32 v120, v170
	v_mov_b32_e32 v121, v171
	v_lshlrev_b32_e32 v122, 16, v120
	v_and_b32_e32 v123, 0xffff0000, v120
	v_lshlrev_b32_e32 v120, 16, v121
	v_and_b32_e32 v121, 0xffff0000, v121
	v_pk_add_f32 v[116:117], v[116:117], v[122:123]
	v_pk_add_f32 v[118:119], v[118:119], v[120:121]
	v_cvt_pk_bf16_f32 v116, v116, v117
	v_cvt_pk_bf16_f32 v117, v118, v119
	global_store_dwordx2 v[138:139], v[116:117], off offset:256
	v_lshlrev_b32_e32 v118, 16, v116
	v_and_b32_e32 v116, 0xffff0000, v116
	v_lshlrev_b32_e32 v119, 16, v117
	v_and_b32_e32 v117, 0xffff0000, v117
	v_mul_f32_e32 v116, v116, v116
	v_mul_f32_e32 v117, v117, v117
	v_fmac_f32_e32 v116, v118, v118
	v_fmac_f32_e32 v117, v119, v119
	v_add_f32_e32 v116, v116, v117
	v_add_f32_e32 v120, v124, v116
	v_mov_b32_e32 v116, v172
	v_mov_b32_e32 v117, v173
	v_lshlrev_b32_e32 v118, 16, v116
	v_and_b32_e32 v119, 0xffff0000, v116
	v_lshlrev_b32_e32 v116, 16, v117
	v_and_b32_e32 v117, 0xffff0000, v117
	v_pk_add_f32 v[112:113], v[112:113], v[118:119]
	v_pk_add_f32 v[114:115], v[114:115], v[116:117]
	v_cvt_pk_bf16_f32 v112, v112, v113
	v_cvt_pk_bf16_f32 v113, v114, v115
	global_store_dwordx2 v[138:139], v[112:113], off offset:288
	v_lshlrev_b32_e32 v114, 16, v112
	v_and_b32_e32 v112, 0xffff0000, v112
	v_lshlrev_b32_e32 v115, 16, v113
	v_and_b32_e32 v113, 0xffff0000, v113
	v_mul_f32_e32 v112, v112, v112
	v_mul_f32_e32 v113, v113, v113
	v_fmac_f32_e32 v112, v114, v114
	v_fmac_f32_e32 v113, v115, v115
	v_add_f32_e32 v112, v112, v113
	v_add_f32_e32 v112, v120, v112
	ds_bpermute_b32 v113, v144, v112
	s_waitcnt lgkmcnt(0)
	v_add_f32_e32 v112, v112, v113
	ds_bpermute_b32 v113, v145, v112
	s_and_saveexec_b64 s[34:35], s[38:39]
	s_cbranch_execz .LBB0_1992
	v_lshlrev_b64 v[114:115], 6, v[136:137]
	v_lshl_add_u64 v[114:115], s[22:23], 0, v[114:115]
	v_lshl_add_u64 v[114:115], s[30:31], 2, v[114:115]
	s_lshl_b32 s66, s54, 2
	v_lshl_add_u64 v[114:115], v[114:115], 0, s[66:67]
	s_waitcnt lgkmcnt(0)
	v_add_f32_e32 v112, v112, v113
	global_store_dword v[114:115], v112, off
.LBB0_1992:
	s_or_b64 exec, exec, s[34:35]
	v_or_b32_e32 v112, 16, v136
	s_waitcnt lgkmcnt(0)
	v_ashrrev_i32_e32 v113, 31, v112
	v_lshlrev_b64 v[114:115], 11, v[112:113]
	v_lshl_add_u64 v[114:115], s[20:21], 0, v[114:115]
	v_lshl_add_u64 v[114:115], v[134:135], 1, v[114:115]
	v_mov_b32_e32 v116, v174
	v_mov_b32_e32 v117, v175
	v_lshlrev_b32_e32 v118, 16, v116
	v_and_b32_e32 v119, 0xffff0000, v116
	v_lshlrev_b32_e32 v116, 16, v117
	v_and_b32_e32 v117, 0xffff0000, v117
	v_pk_add_f32 v[108:109], v[108:109], v[118:119]
	v_pk_add_f32 v[110:111], v[110:111], v[116:117]
	v_cvt_pk_bf16_f32 v108, v108, v109
	v_cvt_pk_bf16_f32 v109, v110, v111
	global_store_dwordx2 v[114:115], v[108:109], off
	v_lshlrev_b32_e32 v110, 16, v108
	v_and_b32_e32 v108, 0xffff0000, v108
	v_lshlrev_b32_e32 v111, 16, v109
	v_and_b32_e32 v109, 0xffff0000, v109
	v_mul_f32_e32 v108, v108, v108
	v_mul_f32_e32 v109, v109, v109
	v_fmac_f32_e32 v108, v110, v110
	v_fmac_f32_e32 v109, v111, v111
	v_add_f32_e32 v116, v108, v109
	v_mov_b32_e32 v108, v176
	v_mov_b32_e32 v109, v177
	v_lshlrev_b32_e32 v110, 16, v108
	v_and_b32_e32 v111, 0xffff0000, v108
	v_lshlrev_b32_e32 v108, 16, v109
	v_and_b32_e32 v109, 0xffff0000, v109
	v_pk_add_f32 v[104:105], v[104:105], v[110:111]
	v_pk_add_f32 v[106:107], v[106:107], v[108:109]
	v_cvt_pk_bf16_f32 v104, v104, v105
	v_cvt_pk_bf16_f32 v105, v106, v107
	global_store_dwordx2 v[114:115], v[104:105], off offset:32
	v_lshlrev_b32_e32 v106, 16, v104
	v_and_b32_e32 v104, 0xffff0000, v104
	v_lshlrev_b32_e32 v107, 16, v105
	v_and_b32_e32 v105, 0xffff0000, v105
	v_mul_f32_e32 v104, v104, v104
	v_mul_f32_e32 v105, v105, v105
	v_fmac_f32_e32 v104, v106, v106
	v_fmac_f32_e32 v105, v107, v107
	v_add_f32_e32 v104, v104, v105
	v_add_f32_e32 v108, v116, v104
	v_mov_b32_e32 v104, v178
	v_mov_b32_e32 v105, v179
	v_lshlrev_b32_e32 v106, 16, v104
	v_and_b32_e32 v107, 0xffff0000, v104
	v_lshlrev_b32_e32 v104, 16, v105
	v_and_b32_e32 v105, 0xffff0000, v105
	v_pk_add_f32 v[100:101], v[100:101], v[106:107]
	v_pk_add_f32 v[102:103], v[102:103], v[104:105]
	v_cvt_pk_bf16_f32 v100, v100, v101
	v_cvt_pk_bf16_f32 v101, v102, v103
	global_store_dwordx2 v[114:115], v[100:101], off offset:256
	v_lshlrev_b32_e32 v102, 16, v100
	v_and_b32_e32 v100, 0xffff0000, v100
	v_lshlrev_b32_e32 v103, 16, v101
	v_and_b32_e32 v101, 0xffff0000, v101
	v_mul_f32_e32 v100, v100, v100
	v_mul_f32_e32 v101, v101, v101
	v_fmac_f32_e32 v100, v102, v102
	v_fmac_f32_e32 v101, v103, v103
	v_add_f32_e32 v100, v100, v101
	v_add_f32_e32 v104, v108, v100
	v_mov_b32_e32 v100, v180
	v_mov_b32_e32 v101, v181
	v_lshlrev_b32_e32 v102, 16, v100
	v_and_b32_e32 v103, 0xffff0000, v100
	v_lshlrev_b32_e32 v100, 16, v101
	v_and_b32_e32 v101, 0xffff0000, v101
	v_pk_add_f32 v[96:97], v[96:97], v[102:103]
	v_pk_add_f32 v[98:99], v[98:99], v[100:101]
	v_cvt_pk_bf16_f32 v96, v96, v97
	v_cvt_pk_bf16_f32 v97, v98, v99
	global_store_dwordx2 v[114:115], v[96:97], off offset:288
	v_lshlrev_b32_e32 v98, 16, v96
	v_and_b32_e32 v96, 0xffff0000, v96
	v_lshlrev_b32_e32 v99, 16, v97
	v_and_b32_e32 v97, 0xffff0000, v97
	v_mul_f32_e32 v96, v96, v96
	v_mul_f32_e32 v97, v97, v97
	v_fmac_f32_e32 v96, v98, v98
	v_fmac_f32_e32 v97, v99, v99
	v_add_f32_e32 v96, v96, v97
	v_add_f32_e32 v96, v104, v96
	ds_bpermute_b32 v97, v144, v96
	s_waitcnt lgkmcnt(0)
	v_add_f32_e32 v96, v96, v97
	ds_bpermute_b32 v97, v145, v96
	s_and_saveexec_b64 s[34:35], s[38:39]
	s_cbranch_execz .LBB0_1994
	v_lshlrev_b64 v[98:99], 6, v[112:113]
	v_lshl_add_u64 v[98:99], s[22:23], 0, v[98:99]
	v_lshl_add_u64 v[98:99], s[30:31], 2, v[98:99]
	s_lshl_b32 s66, s54, 2
	v_lshl_add_u64 v[98:99], v[98:99], 0, s[66:67]
	s_waitcnt lgkmcnt(0)
	v_add_f32_e32 v96, v96, v97
	global_store_dword v[98:99], v96, off
.LBB0_1994:
	s_or_b64 exec, exec, s[34:35]
	v_or_b32_e32 v96, 32, v136
	s_waitcnt lgkmcnt(0)
	v_ashrrev_i32_e32 v97, 31, v96
	v_lshlrev_b64 v[98:99], 11, v[96:97]
	v_lshl_add_u64 v[98:99], s[20:21], 0, v[98:99]
	v_lshl_add_u64 v[98:99], v[134:135], 1, v[98:99]
	v_mov_b32_e32 v100, v182
	v_mov_b32_e32 v101, v183
	v_lshlrev_b32_e32 v102, 16, v100
	v_and_b32_e32 v103, 0xffff0000, v100
	v_lshlrev_b32_e32 v100, 16, v101
	v_and_b32_e32 v101, 0xffff0000, v101
	v_pk_add_f32 v[92:93], v[92:93], v[102:103]
	v_pk_add_f32 v[94:95], v[94:95], v[100:101]
	v_cvt_pk_bf16_f32 v92, v92, v93
	v_cvt_pk_bf16_f32 v93, v94, v95
	global_store_dwordx2 v[98:99], v[92:93], off
	v_lshlrev_b32_e32 v94, 16, v92
	v_and_b32_e32 v92, 0xffff0000, v92
	v_lshlrev_b32_e32 v95, 16, v93
	v_and_b32_e32 v93, 0xffff0000, v93
	v_mul_f32_e32 v92, v92, v92
	v_mul_f32_e32 v93, v93, v93
	v_fmac_f32_e32 v92, v94, v94
	v_fmac_f32_e32 v93, v95, v95
	v_add_f32_e32 v100, v92, v93
	v_mov_b32_e32 v92, v184
	v_mov_b32_e32 v93, v185
	v_lshlrev_b32_e32 v94, 16, v92
	v_and_b32_e32 v95, 0xffff0000, v92
	v_lshlrev_b32_e32 v92, 16, v93
	v_and_b32_e32 v93, 0xffff0000, v93
	v_pk_add_f32 v[88:89], v[88:89], v[94:95]
	v_pk_add_f32 v[90:91], v[90:91], v[92:93]
	v_cvt_pk_bf16_f32 v88, v88, v89
	v_cvt_pk_bf16_f32 v89, v90, v91
	global_store_dwordx2 v[98:99], v[88:89], off offset:32
	v_lshlrev_b32_e32 v90, 16, v88
	v_and_b32_e32 v88, 0xffff0000, v88
	v_lshlrev_b32_e32 v91, 16, v89
	v_and_b32_e32 v89, 0xffff0000, v89
	v_mul_f32_e32 v88, v88, v88
	v_mul_f32_e32 v89, v89, v89
	v_fmac_f32_e32 v88, v90, v90
	v_fmac_f32_e32 v89, v91, v91
	v_add_f32_e32 v88, v88, v89
	v_add_f32_e32 v92, v100, v88
	v_mov_b32_e32 v88, v186
	v_mov_b32_e32 v89, v187
	v_lshlrev_b32_e32 v90, 16, v88
	v_and_b32_e32 v91, 0xffff0000, v88
	v_lshlrev_b32_e32 v88, 16, v89
	v_and_b32_e32 v89, 0xffff0000, v89
	v_pk_add_f32 v[84:85], v[84:85], v[90:91]
	v_pk_add_f32 v[86:87], v[86:87], v[88:89]
	v_cvt_pk_bf16_f32 v84, v84, v85
	v_cvt_pk_bf16_f32 v85, v86, v87
	global_store_dwordx2 v[98:99], v[84:85], off offset:256
	v_lshlrev_b32_e32 v86, 16, v84
	v_and_b32_e32 v84, 0xffff0000, v84
	v_lshlrev_b32_e32 v87, 16, v85
	v_and_b32_e32 v85, 0xffff0000, v85
	v_mul_f32_e32 v84, v84, v84
	v_mul_f32_e32 v85, v85, v85
	v_fmac_f32_e32 v84, v86, v86
	v_fmac_f32_e32 v85, v87, v87
	v_add_f32_e32 v84, v84, v85
	v_add_f32_e32 v88, v92, v84
	v_mov_b32_e32 v84, v188
	v_mov_b32_e32 v85, v189
	v_lshlrev_b32_e32 v86, 16, v84
	v_and_b32_e32 v87, 0xffff0000, v84
	v_lshlrev_b32_e32 v84, 16, v85
	v_and_b32_e32 v85, 0xffff0000, v85
	v_pk_add_f32 v[80:81], v[80:81], v[86:87]
	v_pk_add_f32 v[82:83], v[82:83], v[84:85]
	v_cvt_pk_bf16_f32 v80, v80, v81
	v_cvt_pk_bf16_f32 v81, v82, v83
	global_store_dwordx2 v[98:99], v[80:81], off offset:288
	v_lshlrev_b32_e32 v82, 16, v80
	v_and_b32_e32 v80, 0xffff0000, v80
	v_lshlrev_b32_e32 v83, 16, v81
	v_and_b32_e32 v81, 0xffff0000, v81
	v_mul_f32_e32 v80, v80, v80
	v_mul_f32_e32 v81, v81, v81
	v_fmac_f32_e32 v80, v82, v82
	v_fmac_f32_e32 v81, v83, v83
	v_add_f32_e32 v80, v80, v81
	v_add_f32_e32 v80, v88, v80
	ds_bpermute_b32 v81, v144, v80
	s_waitcnt lgkmcnt(0)
	v_add_f32_e32 v80, v80, v81
	ds_bpermute_b32 v81, v145, v80
	s_and_saveexec_b64 s[34:35], s[38:39]
	s_cbranch_execz .LBB0_1996
	v_lshlrev_b64 v[82:83], 6, v[96:97]
	v_lshl_add_u64 v[82:83], s[22:23], 0, v[82:83]
	v_lshl_add_u64 v[82:83], s[30:31], 2, v[82:83]
	s_lshl_b32 s66, s54, 2
	v_lshl_add_u64 v[82:83], v[82:83], 0, s[66:67]
	s_waitcnt lgkmcnt(0)
	v_add_f32_e32 v80, v80, v81
	global_store_dword v[82:83], v80, off
.LBB0_1996:
	s_or_b64 exec, exec, s[34:35]
	v_or_b32_e32 v80, 48, v136
	s_waitcnt lgkmcnt(0)
	v_ashrrev_i32_e32 v81, 31, v80
	v_lshlrev_b64 v[82:83], 11, v[80:81]
	v_lshl_add_u64 v[82:83], s[20:21], 0, v[82:83]
	v_lshl_add_u64 v[82:83], v[134:135], 1, v[82:83]
	v_mov_b32_e32 v84, v190
	v_mov_b32_e32 v85, v191
	v_lshlrev_b32_e32 v86, 16, v84
	v_and_b32_e32 v87, 0xffff0000, v84
	v_lshlrev_b32_e32 v84, 16, v85
	v_and_b32_e32 v85, 0xffff0000, v85
	v_pk_add_f32 v[76:77], v[76:77], v[86:87]
	v_pk_add_f32 v[78:79], v[78:79], v[84:85]
	v_cvt_pk_bf16_f32 v76, v76, v77
	v_cvt_pk_bf16_f32 v77, v78, v79
	global_store_dwordx2 v[82:83], v[76:77], off
	v_lshlrev_b32_e32 v78, 16, v76
	v_and_b32_e32 v76, 0xffff0000, v76
	v_lshlrev_b32_e32 v79, 16, v77
	v_and_b32_e32 v77, 0xffff0000, v77
	v_mul_f32_e32 v76, v76, v76
	v_mul_f32_e32 v77, v77, v77
	v_fmac_f32_e32 v76, v78, v78
	v_fmac_f32_e32 v77, v79, v79
	v_add_f32_e32 v84, v76, v77
	v_mov_b32_e32 v76, v192
	v_mov_b32_e32 v77, v193
	v_lshlrev_b32_e32 v78, 16, v76
	v_and_b32_e32 v79, 0xffff0000, v76
	v_lshlrev_b32_e32 v76, 16, v77
	v_and_b32_e32 v77, 0xffff0000, v77
	v_pk_add_f32 v[72:73], v[72:73], v[78:79]
	v_pk_add_f32 v[74:75], v[74:75], v[76:77]
	v_cvt_pk_bf16_f32 v72, v72, v73
	v_cvt_pk_bf16_f32 v73, v74, v75
	global_store_dwordx2 v[82:83], v[72:73], off offset:32
	v_lshlrev_b32_e32 v74, 16, v72
	v_and_b32_e32 v72, 0xffff0000, v72
	v_lshlrev_b32_e32 v75, 16, v73
	v_and_b32_e32 v73, 0xffff0000, v73
	v_mul_f32_e32 v72, v72, v72
	v_mul_f32_e32 v73, v73, v73
	v_fmac_f32_e32 v72, v74, v74
	v_fmac_f32_e32 v73, v75, v75
	v_add_f32_e32 v72, v72, v73
	v_add_f32_e32 v76, v84, v72
	v_mov_b32_e32 v72, v194
	v_mov_b32_e32 v73, v195
	v_lshlrev_b32_e32 v74, 16, v72
	v_and_b32_e32 v75, 0xffff0000, v72
	v_lshlrev_b32_e32 v72, 16, v73
	v_and_b32_e32 v73, 0xffff0000, v73
	v_pk_add_f32 v[68:69], v[68:69], v[74:75]
	v_pk_add_f32 v[70:71], v[70:71], v[72:73]
	v_cvt_pk_bf16_f32 v68, v68, v69
	v_cvt_pk_bf16_f32 v69, v70, v71
	global_store_dwordx2 v[82:83], v[68:69], off offset:256
	v_lshlrev_b32_e32 v70, 16, v68
	v_and_b32_e32 v68, 0xffff0000, v68
	v_lshlrev_b32_e32 v71, 16, v69
	v_and_b32_e32 v69, 0xffff0000, v69
	v_mul_f32_e32 v68, v68, v68
	v_mul_f32_e32 v69, v69, v69
	v_fmac_f32_e32 v68, v70, v70
	v_fmac_f32_e32 v69, v71, v71
	v_add_f32_e32 v68, v68, v69
	v_add_f32_e32 v72, v76, v68
	v_mov_b32_e32 v68, v196
	v_mov_b32_e32 v69, v197
	v_lshlrev_b32_e32 v70, 16, v68
	v_and_b32_e32 v71, 0xffff0000, v68
	v_lshlrev_b32_e32 v68, 16, v69
	v_and_b32_e32 v69, 0xffff0000, v69
	v_pk_add_f32 v[64:65], v[64:65], v[70:71]
	v_pk_add_f32 v[66:67], v[66:67], v[68:69]
	v_cvt_pk_bf16_f32 v64, v64, v65
	v_cvt_pk_bf16_f32 v65, v66, v67
	global_store_dwordx2 v[82:83], v[64:65], off offset:288
	v_lshlrev_b32_e32 v66, 16, v64
	v_and_b32_e32 v64, 0xffff0000, v64
	v_lshlrev_b32_e32 v67, 16, v65
	v_and_b32_e32 v65, 0xffff0000, v65
	v_mul_f32_e32 v64, v64, v64
	v_mul_f32_e32 v65, v65, v65
	v_fmac_f32_e32 v64, v66, v66
	v_fmac_f32_e32 v65, v67, v67
	v_add_f32_e32 v64, v64, v65
	v_add_f32_e32 v64, v72, v64
	ds_bpermute_b32 v65, v144, v64
	s_waitcnt lgkmcnt(0)
	v_add_f32_e32 v64, v64, v65
	ds_bpermute_b32 v65, v145, v64
	s_and_saveexec_b64 s[34:35], s[38:39]
	s_cbranch_execz .LBB0_1998
	v_lshlrev_b64 v[66:67], 6, v[80:81]
	v_lshl_add_u64 v[66:67], s[22:23], 0, v[66:67]
	v_lshl_add_u64 v[66:67], s[30:31], 2, v[66:67]
	s_lshl_b32 s66, s54, 2
	v_lshl_add_u64 v[66:67], v[66:67], 0, s[66:67]
	s_waitcnt lgkmcnt(0)
	v_add_f32_e32 v64, v64, v65
	global_store_dword v[66:67], v64, off
.LBB0_1998:
	s_or_b64 exec, exec, s[34:35]
	v_add_u32_e32 v64, 0x80, v136
	s_waitcnt lgkmcnt(0)
	v_ashrrev_i32_e32 v65, 31, v64
	v_lshlrev_b64 v[66:67], 11, v[64:65]
	v_lshl_add_u64 v[66:67], s[20:21], 0, v[66:67]
	v_lshl_add_u64 v[66:67], v[134:135], 1, v[66:67]
	v_mov_b32_e32 v68, v198
	v_mov_b32_e32 v69, v199
	v_lshlrev_b32_e32 v70, 16, v68
	v_and_b32_e32 v71, 0xffff0000, v68
	v_lshlrev_b32_e32 v68, 16, v69
	v_and_b32_e32 v69, 0xffff0000, v69
	v_pk_add_f32 v[60:61], v[60:61], v[70:71]
	v_pk_add_f32 v[62:63], v[62:63], v[68:69]
	v_cvt_pk_bf16_f32 v60, v60, v61
	v_cvt_pk_bf16_f32 v61, v62, v63
	global_store_dwordx2 v[66:67], v[60:61], off
	v_lshlrev_b32_e32 v62, 16, v60
	v_and_b32_e32 v60, 0xffff0000, v60
	v_lshlrev_b32_e32 v63, 16, v61
	v_and_b32_e32 v61, 0xffff0000, v61
	v_mul_f32_e32 v60, v60, v60
	v_mul_f32_e32 v61, v61, v61
	v_fmac_f32_e32 v60, v62, v62
	v_fmac_f32_e32 v61, v63, v63
	v_add_f32_e32 v68, v60, v61
	v_mov_b32_e32 v60, v200
	v_mov_b32_e32 v61, v201
	v_lshlrev_b32_e32 v62, 16, v60
	v_and_b32_e32 v63, 0xffff0000, v60
	v_lshlrev_b32_e32 v60, 16, v61
	v_and_b32_e32 v61, 0xffff0000, v61
	v_pk_add_f32 v[56:57], v[56:57], v[62:63]
	v_pk_add_f32 v[58:59], v[58:59], v[60:61]
	v_cvt_pk_bf16_f32 v56, v56, v57
	v_cvt_pk_bf16_f32 v57, v58, v59
	global_store_dwordx2 v[66:67], v[56:57], off offset:32
	v_lshlrev_b32_e32 v58, 16, v56
	v_and_b32_e32 v56, 0xffff0000, v56
	v_lshlrev_b32_e32 v59, 16, v57
	v_and_b32_e32 v57, 0xffff0000, v57
	v_mul_f32_e32 v56, v56, v56
	v_mul_f32_e32 v57, v57, v57
	v_fmac_f32_e32 v56, v58, v58
	v_fmac_f32_e32 v57, v59, v59
	v_add_f32_e32 v56, v56, v57
	v_add_f32_e32 v60, v68, v56
	v_mov_b32_e32 v56, v202
	v_mov_b32_e32 v57, v203
	v_lshlrev_b32_e32 v58, 16, v56
	v_and_b32_e32 v59, 0xffff0000, v56
	v_lshlrev_b32_e32 v56, 16, v57
	v_and_b32_e32 v57, 0xffff0000, v57
	v_pk_add_f32 v[52:53], v[52:53], v[58:59]
	v_pk_add_f32 v[54:55], v[54:55], v[56:57]
	v_cvt_pk_bf16_f32 v52, v52, v53
	v_cvt_pk_bf16_f32 v53, v54, v55
	global_store_dwordx2 v[66:67], v[52:53], off offset:256
	v_lshlrev_b32_e32 v54, 16, v52
	v_and_b32_e32 v52, 0xffff0000, v52
	v_lshlrev_b32_e32 v55, 16, v53
	v_and_b32_e32 v53, 0xffff0000, v53
	v_mul_f32_e32 v52, v52, v52
	v_mul_f32_e32 v53, v53, v53
	v_fmac_f32_e32 v52, v54, v54
	v_fmac_f32_e32 v53, v55, v55
	v_add_f32_e32 v52, v52, v53
	v_add_f32_e32 v56, v60, v52
	v_mov_b32_e32 v52, v204
	v_mov_b32_e32 v53, v205
	v_lshlrev_b32_e32 v54, 16, v52
	v_and_b32_e32 v55, 0xffff0000, v52
	v_lshlrev_b32_e32 v52, 16, v53
	v_and_b32_e32 v53, 0xffff0000, v53
	v_pk_add_f32 v[48:49], v[48:49], v[54:55]
	v_pk_add_f32 v[50:51], v[50:51], v[52:53]
	v_cvt_pk_bf16_f32 v48, v48, v49
	v_cvt_pk_bf16_f32 v49, v50, v51
	global_store_dwordx2 v[66:67], v[48:49], off offset:288
	v_lshlrev_b32_e32 v50, 16, v48
	v_and_b32_e32 v48, 0xffff0000, v48
	v_lshlrev_b32_e32 v51, 16, v49
	v_and_b32_e32 v49, 0xffff0000, v49
	v_mul_f32_e32 v48, v48, v48
	v_mul_f32_e32 v49, v49, v49
	v_fmac_f32_e32 v48, v50, v50
	v_fmac_f32_e32 v49, v51, v51
	v_add_f32_e32 v48, v48, v49
	v_add_f32_e32 v48, v56, v48
	ds_bpermute_b32 v49, v144, v48
	s_waitcnt lgkmcnt(0)
	v_add_f32_e32 v48, v48, v49
	ds_bpermute_b32 v49, v145, v48
	s_and_saveexec_b64 s[34:35], s[38:39]
	s_cbranch_execz .LBB0_2000
	v_lshlrev_b64 v[50:51], 6, v[64:65]
	v_lshl_add_u64 v[50:51], s[22:23], 0, v[50:51]
	v_lshl_add_u64 v[50:51], s[30:31], 2, v[50:51]
	s_lshl_b32 s66, s54, 2
	v_lshl_add_u64 v[50:51], v[50:51], 0, s[66:67]
	s_waitcnt lgkmcnt(0)
	v_add_f32_e32 v48, v48, v49
	global_store_dword v[50:51], v48, off
.LBB0_2000:
	s_or_b64 exec, exec, s[34:35]
	v_add_u32_e32 v48, 0x90, v136
	s_waitcnt lgkmcnt(0)
	v_ashrrev_i32_e32 v49, 31, v48
	v_lshlrev_b64 v[50:51], 11, v[48:49]
	v_lshl_add_u64 v[50:51], s[20:21], 0, v[50:51]
	v_lshl_add_u64 v[50:51], v[134:135], 1, v[50:51]
	v_mov_b32_e32 v52, v206
	v_mov_b32_e32 v53, v207
	v_lshlrev_b32_e32 v54, 16, v52
	v_and_b32_e32 v55, 0xffff0000, v52
	v_lshlrev_b32_e32 v52, 16, v53
	v_and_b32_e32 v53, 0xffff0000, v53
	v_pk_add_f32 v[44:45], v[44:45], v[54:55]
	v_pk_add_f32 v[46:47], v[46:47], v[52:53]
	v_cvt_pk_bf16_f32 v44, v44, v45
	v_cvt_pk_bf16_f32 v45, v46, v47
	global_store_dwordx2 v[50:51], v[44:45], off
	v_lshlrev_b32_e32 v46, 16, v44
	v_and_b32_e32 v44, 0xffff0000, v44
	v_lshlrev_b32_e32 v47, 16, v45
	v_and_b32_e32 v45, 0xffff0000, v45
	v_mul_f32_e32 v44, v44, v44
	v_mul_f32_e32 v45, v45, v45
	v_fmac_f32_e32 v44, v46, v46
	v_fmac_f32_e32 v45, v47, v47
	v_add_f32_e32 v52, v44, v45
	v_mov_b32_e32 v44, v222
	v_mov_b32_e32 v45, v223
	v_lshlrev_b32_e32 v46, 16, v44
	v_and_b32_e32 v47, 0xffff0000, v44
	v_lshlrev_b32_e32 v44, 16, v45
	v_and_b32_e32 v45, 0xffff0000, v45
	v_pk_add_f32 v[40:41], v[40:41], v[46:47]
	v_pk_add_f32 v[42:43], v[42:43], v[44:45]
	v_cvt_pk_bf16_f32 v40, v40, v41
	v_cvt_pk_bf16_f32 v41, v42, v43
	global_store_dwordx2 v[50:51], v[40:41], off offset:32
	v_lshlrev_b32_e32 v42, 16, v40
	v_and_b32_e32 v40, 0xffff0000, v40
	v_lshlrev_b32_e32 v43, 16, v41
	v_and_b32_e32 v41, 0xffff0000, v41
	v_mul_f32_e32 v40, v40, v40
	v_mul_f32_e32 v41, v41, v41
	v_fmac_f32_e32 v40, v42, v42
	v_fmac_f32_e32 v41, v43, v43
	v_add_f32_e32 v40, v40, v41
	v_add_f32_e32 v44, v52, v40
	v_mov_b32_e32 v40, v224
	v_mov_b32_e32 v41, v225
	v_lshlrev_b32_e32 v42, 16, v40
	v_and_b32_e32 v43, 0xffff0000, v40
	v_lshlrev_b32_e32 v40, 16, v41
	v_and_b32_e32 v41, 0xffff0000, v41
	v_pk_add_f32 v[36:37], v[36:37], v[42:43]
	v_pk_add_f32 v[38:39], v[38:39], v[40:41]
	v_cvt_pk_bf16_f32 v36, v36, v37
	v_cvt_pk_bf16_f32 v37, v38, v39
	global_store_dwordx2 v[50:51], v[36:37], off offset:256
	v_lshlrev_b32_e32 v38, 16, v36
	v_and_b32_e32 v36, 0xffff0000, v36
	v_lshlrev_b32_e32 v39, 16, v37
	v_and_b32_e32 v37, 0xffff0000, v37
	v_mul_f32_e32 v36, v36, v36
	v_mul_f32_e32 v37, v37, v37
	v_fmac_f32_e32 v36, v38, v38
	v_fmac_f32_e32 v37, v39, v39
	v_add_f32_e32 v36, v36, v37
	v_add_f32_e32 v40, v44, v36
	v_mov_b32_e32 v36, v226
	v_mov_b32_e32 v37, v227
	v_lshlrev_b32_e32 v38, 16, v36
	v_and_b32_e32 v39, 0xffff0000, v36
	v_lshlrev_b32_e32 v36, 16, v37
	v_and_b32_e32 v37, 0xffff0000, v37
	v_pk_add_f32 v[32:33], v[32:33], v[38:39]
	v_pk_add_f32 v[34:35], v[34:35], v[36:37]
	v_cvt_pk_bf16_f32 v32, v32, v33
	v_cvt_pk_bf16_f32 v33, v34, v35
	global_store_dwordx2 v[50:51], v[32:33], off offset:288
	v_lshlrev_b32_e32 v34, 16, v32
	v_and_b32_e32 v32, 0xffff0000, v32
	v_lshlrev_b32_e32 v35, 16, v33
	v_and_b32_e32 v33, 0xffff0000, v33
	v_mul_f32_e32 v32, v32, v32
	v_mul_f32_e32 v33, v33, v33
	v_fmac_f32_e32 v32, v34, v34
	v_fmac_f32_e32 v33, v35, v35
	v_add_f32_e32 v32, v32, v33
	v_add_f32_e32 v32, v40, v32
	ds_bpermute_b32 v33, v144, v32
	s_waitcnt lgkmcnt(0)
	v_add_f32_e32 v32, v32, v33
	ds_bpermute_b32 v33, v145, v32
	s_and_saveexec_b64 s[34:35], s[38:39]
	s_cbranch_execz .LBB0_2002
	v_lshlrev_b64 v[34:35], 6, v[48:49]
	v_lshl_add_u64 v[34:35], s[22:23], 0, v[34:35]
	v_lshl_add_u64 v[34:35], s[30:31], 2, v[34:35]
	s_lshl_b32 s66, s54, 2
	v_lshl_add_u64 v[34:35], v[34:35], 0, s[66:67]
	s_waitcnt lgkmcnt(0)
	v_add_f32_e32 v32, v32, v33
	global_store_dword v[34:35], v32, off
.LBB0_2002:
	s_or_b64 exec, exec, s[34:35]
	v_add_u32_e32 v32, 0xa0, v136
	s_waitcnt lgkmcnt(0)
	v_ashrrev_i32_e32 v33, 31, v32
	v_lshlrev_b64 v[34:35], 11, v[32:33]
	v_lshl_add_u64 v[34:35], s[20:21], 0, v[34:35]
	v_lshl_add_u64 v[34:35], v[134:135], 1, v[34:35]
	v_mov_b32_e32 v36, v228
	v_mov_b32_e32 v37, v229
	v_lshlrev_b32_e32 v38, 16, v36
	v_and_b32_e32 v39, 0xffff0000, v36
	v_lshlrev_b32_e32 v36, 16, v37
	v_and_b32_e32 v37, 0xffff0000, v37
	v_pk_add_f32 v[28:29], v[28:29], v[38:39]
	v_pk_add_f32 v[30:31], v[30:31], v[36:37]
	v_cvt_pk_bf16_f32 v28, v28, v29
	v_cvt_pk_bf16_f32 v29, v30, v31
	global_store_dwordx2 v[34:35], v[28:29], off
	v_lshlrev_b32_e32 v30, 16, v28
	v_and_b32_e32 v28, 0xffff0000, v28
	v_lshlrev_b32_e32 v31, 16, v29
	v_and_b32_e32 v29, 0xffff0000, v29
	v_mul_f32_e32 v28, v28, v28
	v_mul_f32_e32 v29, v29, v29
	v_fmac_f32_e32 v28, v30, v30
	v_fmac_f32_e32 v29, v31, v31
	v_add_f32_e32 v36, v28, v29
	v_mov_b32_e32 v28, v230
	v_mov_b32_e32 v29, v231
	v_lshlrev_b32_e32 v30, 16, v28
	v_and_b32_e32 v31, 0xffff0000, v28
	v_lshlrev_b32_e32 v28, 16, v29
	v_and_b32_e32 v29, 0xffff0000, v29
	v_pk_add_f32 v[24:25], v[24:25], v[30:31]
	v_pk_add_f32 v[26:27], v[26:27], v[28:29]
	v_cvt_pk_bf16_f32 v24, v24, v25
	v_cvt_pk_bf16_f32 v25, v26, v27
	global_store_dwordx2 v[34:35], v[24:25], off offset:32
	v_lshlrev_b32_e32 v26, 16, v24
	v_and_b32_e32 v24, 0xffff0000, v24
	v_lshlrev_b32_e32 v27, 16, v25
	v_and_b32_e32 v25, 0xffff0000, v25
	v_mul_f32_e32 v24, v24, v24
	v_mul_f32_e32 v25, v25, v25
	v_fmac_f32_e32 v24, v26, v26
	v_fmac_f32_e32 v25, v27, v27
	v_add_f32_e32 v24, v24, v25
	v_add_f32_e32 v28, v36, v24
	v_mov_b32_e32 v24, v232
	v_mov_b32_e32 v25, v233
	v_lshlrev_b32_e32 v26, 16, v24
	v_and_b32_e32 v27, 0xffff0000, v24
	v_lshlrev_b32_e32 v24, 16, v25
	v_and_b32_e32 v25, 0xffff0000, v25
	v_pk_add_f32 v[20:21], v[20:21], v[26:27]
	v_pk_add_f32 v[22:23], v[22:23], v[24:25]
	v_cvt_pk_bf16_f32 v20, v20, v21
	v_cvt_pk_bf16_f32 v21, v22, v23
	global_store_dwordx2 v[34:35], v[20:21], off offset:256
	v_lshlrev_b32_e32 v22, 16, v20
	v_and_b32_e32 v20, 0xffff0000, v20
	v_lshlrev_b32_e32 v23, 16, v21
	v_and_b32_e32 v21, 0xffff0000, v21
	v_mul_f32_e32 v20, v20, v20
	v_mul_f32_e32 v21, v21, v21
	v_fmac_f32_e32 v20, v22, v22
	v_fmac_f32_e32 v21, v23, v23
	v_add_f32_e32 v20, v20, v21
	v_add_f32_e32 v24, v28, v20
	v_mov_b32_e32 v20, v234
	v_mov_b32_e32 v21, v235
	v_lshlrev_b32_e32 v22, 16, v20
	v_and_b32_e32 v23, 0xffff0000, v20
	v_lshlrev_b32_e32 v20, 16, v21
	v_and_b32_e32 v21, 0xffff0000, v21
	v_pk_add_f32 v[16:17], v[16:17], v[22:23]
	v_pk_add_f32 v[18:19], v[18:19], v[20:21]
	v_cvt_pk_bf16_f32 v16, v16, v17
	v_cvt_pk_bf16_f32 v17, v18, v19
	global_store_dwordx2 v[34:35], v[16:17], off offset:288
	v_lshlrev_b32_e32 v18, 16, v16
	v_and_b32_e32 v16, 0xffff0000, v16
	v_lshlrev_b32_e32 v19, 16, v17
	v_and_b32_e32 v17, 0xffff0000, v17
	v_mul_f32_e32 v16, v16, v16
	v_mul_f32_e32 v17, v17, v17
	v_fmac_f32_e32 v16, v18, v18
	v_fmac_f32_e32 v17, v19, v19
	v_add_f32_e32 v16, v16, v17
	v_add_f32_e32 v16, v24, v16
	ds_bpermute_b32 v17, v144, v16
	s_waitcnt lgkmcnt(0)
	v_add_f32_e32 v16, v16, v17
	ds_bpermute_b32 v17, v145, v16
	s_and_saveexec_b64 s[34:35], s[38:39]
	s_cbranch_execz .LBB0_2004
	v_lshlrev_b64 v[18:19], 6, v[32:33]
	v_lshl_add_u64 v[18:19], s[22:23], 0, v[18:19]
	v_lshl_add_u64 v[18:19], s[30:31], 2, v[18:19]
	s_lshl_b32 s66, s54, 2
	v_lshl_add_u64 v[18:19], v[18:19], 0, s[66:67]
	s_waitcnt lgkmcnt(0)
	v_add_f32_e32 v16, v16, v17
	global_store_dword v[18:19], v16, off
.LBB0_2004:
	s_or_b64 exec, exec, s[34:35]
	v_add_u32_e32 v16, 0xb0, v136
	s_waitcnt lgkmcnt(0)
	v_ashrrev_i32_e32 v17, 31, v16
	v_lshlrev_b64 v[18:19], 11, v[16:17]
	v_lshl_add_u64 v[18:19], s[20:21], 0, v[18:19]
	v_lshl_add_u64 v[18:19], v[134:135], 1, v[18:19]
	v_mov_b32_e32 v20, v236
	v_mov_b32_e32 v21, v237
	v_lshlrev_b32_e32 v22, 16, v20
	v_and_b32_e32 v23, 0xffff0000, v20
	v_lshlrev_b32_e32 v20, 16, v21
	v_and_b32_e32 v21, 0xffff0000, v21
	v_pk_add_f32 v[12:13], v[12:13], v[22:23]
	v_pk_add_f32 v[14:15], v[14:15], v[20:21]
	v_cvt_pk_bf16_f32 v12, v12, v13
	v_cvt_pk_bf16_f32 v13, v14, v15
	global_store_dwordx2 v[18:19], v[12:13], off
	v_lshlrev_b32_e32 v14, 16, v12
	v_and_b32_e32 v12, 0xffff0000, v12
	v_lshlrev_b32_e32 v15, 16, v13
	v_and_b32_e32 v13, 0xffff0000, v13
	v_mul_f32_e32 v12, v12, v12
	v_mul_f32_e32 v13, v13, v13
	v_fmac_f32_e32 v12, v14, v14
	v_fmac_f32_e32 v13, v15, v15
	v_add_f32_e32 v20, v12, v13
	v_mov_b32_e32 v12, v238
	v_mov_b32_e32 v13, v239
	v_lshlrev_b32_e32 v14, 16, v12
	v_and_b32_e32 v15, 0xffff0000, v12
	v_lshlrev_b32_e32 v12, 16, v13
	v_and_b32_e32 v13, 0xffff0000, v13
	v_pk_add_f32 v[8:9], v[8:9], v[14:15]
	v_pk_add_f32 v[10:11], v[10:11], v[12:13]
	v_cvt_pk_bf16_f32 v8, v8, v9
	v_cvt_pk_bf16_f32 v9, v10, v11
	global_store_dwordx2 v[18:19], v[8:9], off offset:32
	v_lshlrev_b32_e32 v10, 16, v8
	v_and_b32_e32 v8, 0xffff0000, v8
	v_lshlrev_b32_e32 v11, 16, v9
	v_and_b32_e32 v9, 0xffff0000, v9
	v_mul_f32_e32 v8, v8, v8
	v_mul_f32_e32 v9, v9, v9
	v_fmac_f32_e32 v8, v10, v10
	v_fmac_f32_e32 v9, v11, v11
	v_add_f32_e32 v8, v8, v9
	v_add_f32_e32 v12, v20, v8
	v_mov_b32_e32 v8, v240
	v_mov_b32_e32 v9, v241
	v_lshlrev_b32_e32 v10, 16, v8
	v_and_b32_e32 v11, 0xffff0000, v8
	v_lshlrev_b32_e32 v8, 16, v9
	v_and_b32_e32 v9, 0xffff0000, v9
	v_pk_add_f32 v[4:5], v[4:5], v[10:11]
	v_pk_add_f32 v[6:7], v[6:7], v[8:9]
	v_cvt_pk_bf16_f32 v4, v4, v5
	v_cvt_pk_bf16_f32 v5, v6, v7
	global_store_dwordx2 v[18:19], v[4:5], off offset:256
	v_lshlrev_b32_e32 v6, 16, v4
	v_and_b32_e32 v4, 0xffff0000, v4
	v_lshlrev_b32_e32 v7, 16, v5
	v_and_b32_e32 v5, 0xffff0000, v5
	v_mul_f32_e32 v4, v4, v4
	v_mul_f32_e32 v5, v5, v5
	v_fmac_f32_e32 v4, v6, v6
	v_fmac_f32_e32 v5, v7, v7
	v_add_f32_e32 v4, v4, v5
	v_add_f32_e32 v8, v12, v4
	v_mov_b32_e32 v4, v242
	v_mov_b32_e32 v5, v243
	v_lshlrev_b32_e32 v6, 16, v4
	v_and_b32_e32 v7, 0xffff0000, v4
	v_lshlrev_b32_e32 v4, 16, v5
	v_and_b32_e32 v5, 0xffff0000, v5
	v_pk_add_f32 v[0:1], v[0:1], v[6:7]
	v_pk_add_f32 v[2:3], v[2:3], v[4:5]
	v_cvt_pk_bf16_f32 v0, v0, v1
	v_cvt_pk_bf16_f32 v1, v2, v3
	global_store_dwordx2 v[18:19], v[0:1], off offset:288
	v_lshlrev_b32_e32 v2, 16, v0
	v_and_b32_e32 v0, 0xffff0000, v0
	v_lshlrev_b32_e32 v3, 16, v1
	v_and_b32_e32 v1, 0xffff0000, v1
	v_mul_f32_e32 v0, v0, v0
	v_mul_f32_e32 v1, v1, v1
	v_fmac_f32_e32 v0, v2, v2
	v_fmac_f32_e32 v1, v3, v3
	v_add_f32_e32 v0, v0, v1
	v_add_f32_e32 v0, v8, v0
	ds_bpermute_b32 v1, v144, v0
	s_waitcnt lgkmcnt(0)
	v_add_f32_e32 v0, v0, v1
	ds_bpermute_b32 v1, v145, v0
	s_and_saveexec_b64 s[34:35], s[38:39]
	s_cbranch_execz .LBB0_2006
	v_lshlrev_b64 v[2:3], 6, v[16:17]
	v_lshl_add_u64 v[2:3], s[22:23], 0, v[2:3]
	v_lshl_add_u64 v[2:3], s[30:31], 2, v[2:3]
	s_lshl_b32 s66, s54, 2
	v_lshl_add_u64 v[2:3], v[2:3], 0, s[66:67]
	s_waitcnt lgkmcnt(0)
	v_add_f32_e32 v0, v0, v1
	global_store_dword v[2:3], v0, off

.LBB0_2309:
	v_and_b32_e32 v138, 64, v208
	v_xor_b32_e32 v137, 16, v208
	v_add_u32_e32 v138, 64, v138
	v_cmp_lt_i32_e32 vcc, v137, v138
	v_lshl_add_u32 v136, s66, 8, v140
	v_lshl_or_b32 v134, s10, 8, v142
	v_cndmask_b32_e32 v137, v208, v137, vcc
	v_lshlrev_b32_e32 v144, 2, v137
	v_xor_b32_e32 v137, 32, v208
	v_cmp_lt_i32_e32 vcc, v137, v138
	v_ashrrev_i32_e32 v135, 31, v134
	s_lshl_b32 s30, s10, 2
	v_cndmask_b32_e32 v137, v208, v137, vcc
	v_lshlrev_b32_e32 v145, 2, v137
	v_ashrrev_i32_e32 v137, 31, v136
	v_lshlrev_b64 v[138:139], 11, v[136:137]
	v_lshl_add_u64 v[138:139], s[18:19], 0, v[138:139]
	v_lshl_add_u64 v[138:139], v[134:135], 1, v[138:139]
	global_load_dwordx2 v[166:167], v[138:139], off
	global_load_dwordx2 v[168:169], v[138:139], off offset:32
	global_load_dwordx2 v[170:171], v[138:139], off offset:256
	global_load_dwordx2 v[172:173], v[138:139], off offset:288
	v_add_co_u32_e32 v250, vcc, 0x8000, v138
	s_nop 1
	v_addc_co_u32_e32 v251, vcc, 0, v139, vcc
	global_load_dwordx2 v[174:175], v[250:251], off
	global_load_dwordx2 v[176:177], v[250:251], off offset:32
	global_load_dwordx2 v[178:179], v[250:251], off offset:256
	global_load_dwordx2 v[180:181], v[250:251], off offset:288
	v_add_co_u32_e32 v250, vcc, 0x10000, v138
	s_nop 1
	v_addc_co_u32_e32 v251, vcc, 0, v139, vcc
	global_load_dwordx2 v[182:183], v[250:251], off
	global_load_dwordx2 v[184:185], v[250:251], off offset:32
	global_load_dwordx2 v[186:187], v[250:251], off offset:256
	global_load_dwordx2 v[188:189], v[250:251], off offset:288
	v_add_co_u32_e32 v250, vcc, 0x18000, v138
	s_nop 1
	v_addc_co_u32_e32 v251, vcc, 0, v139, vcc
	global_load_dwordx2 v[190:191], v[250:251], off
	global_load_dwordx2 v[192:193], v[250:251], off offset:32
	global_load_dwordx2 v[194:195], v[250:251], off offset:256
	global_load_dwordx2 v[196:197], v[250:251], off offset:288
	v_add_co_u32_e32 v250, vcc, 0x40000, v138
	s_nop 1
	v_addc_co_u32_e32 v251, vcc, 0, v139, vcc
	global_load_dwordx2 v[198:199], v[250:251], off
	global_load_dwordx2 v[200:201], v[250:251], off offset:32
	global_load_dwordx2 v[202:203], v[250:251], off offset:256
	global_load_dwordx2 v[204:205], v[250:251], off offset:288
	v_add_co_u32_e32 v250, vcc, 0x48000, v138
	s_nop 1
	v_addc_co_u32_e32 v251, vcc, 0, v139, vcc
	global_load_dwordx2 v[206:207], v[250:251], off
	global_load_dwordx2 v[222:223], v[250:251], off offset:32
	global_load_dwordx2 v[224:225], v[250:251], off offset:256
	global_load_dwordx2 v[226:227], v[250:251], off offset:288
	v_add_co_u32_e32 v250, vcc, 0x50000, v138
	s_nop 1
	v_addc_co_u32_e32 v251, vcc, 0, v139, vcc
	global_load_dwordx2 v[228:229], v[250:251], off
	global_load_dwordx2 v[230:231], v[250:251], off offset:32
	global_load_dwordx2 v[232:233], v[250:251], off offset:256
	global_load_dwordx2 v[234:235], v[250:251], off offset:288
	v_add_co_u32_e32 v250, vcc, 0x58000, v138
	s_nop 1
	v_addc_co_u32_e32 v251, vcc, 0, v139, vcc
	global_load_dwordx2 v[236:237], v[250:251], off
	global_load_dwordx2 v[238:239], v[250:251], off offset:32
	global_load_dwordx2 v[240:241], v[250:251], off offset:256
	global_load_dwordx2 v[242:243], v[250:251], off offset:288
	s_waitcnt vmcnt(0)
	v_mov_b32_e32 v146, v166
	v_mov_b32_e32 v147, v167
	s_ashr_i32 s31, s30, 31
	v_lshlrev_b32_e32 v148, 16, v146
	v_and_b32_e32 v149, 0xffff0000, v146
	v_lshlrev_b32_e32 v146, 16, v147
	v_and_b32_e32 v147, 0xffff0000, v147
	v_pk_fma_f32 v[124:125], v[124:125], 0.5, v[148:149] op_sel_hi:[1,0,1]
	v_pk_fma_f32 v[126:127], v[126:127], 0.5, v[146:147] op_sel_hi:[1,0,1]
	v_cvt_pk_bf16_f32 v124, v124, v125
	v_cvt_pk_bf16_f32 v125, v126, v127
	global_store_dwordx2 v[138:139], v[124:125], off
	v_lshlrev_b32_e32 v126, 16, v124
	v_and_b32_e32 v124, 0xffff0000, v124
	v_lshlrev_b32_e32 v127, 16, v125
	v_and_b32_e32 v125, 0xffff0000, v125
	v_mul_f32_e32 v124, v124, v124
	v_mul_f32_e32 v125, v125, v125
	v_fmac_f32_e32 v124, v126, v126
	v_fmac_f32_e32 v125, v127, v127
	v_add_f32_e32 v146, v124, v125
	v_mov_b32_e32 v124, v168
	v_mov_b32_e32 v125, v169
	v_lshlrev_b32_e32 v126, 16, v124
	v_and_b32_e32 v127, 0xffff0000, v124
	v_lshlrev_b32_e32 v124, 16, v125
	v_and_b32_e32 v125, 0xffff0000, v125
	v_pk_fma_f32 v[120:121], v[120:121], 0.5, v[126:127] op_sel_hi:[1,0,1]
	v_pk_fma_f32 v[122:123], v[122:123], 0.5, v[124:125] op_sel_hi:[1,0,1]
	v_cvt_pk_bf16_f32 v120, v120, v121
	v_cvt_pk_bf16_f32 v121, v122, v123
	global_store_dwordx2 v[138:139], v[120:121], off offset:32
	v_lshlrev_b32_e32 v122, 16, v120
	v_and_b32_e32 v120, 0xffff0000, v120
	v_lshlrev_b32_e32 v123, 16, v121
	v_and_b32_e32 v121, 0xffff0000, v121
	v_mul_f32_e32 v120, v120, v120
	v_mul_f32_e32 v121, v121, v121
	v_fmac_f32_e32 v120, v122, v122
	v_fmac_f32_e32 v121, v123, v123
	v_add_f32_e32 v120, v120, v121
	v_add_f32_e32 v124, v146, v120
	v_mov_b32_e32 v120, v170
	v_mov_b32_e32 v121, v171
	v_lshlrev_b32_e32 v122, 16, v120
	v_and_b32_e32 v123, 0xffff0000, v120
	v_lshlrev_b32_e32 v120, 16, v121
	v_and_b32_e32 v121, 0xffff0000, v121
	v_pk_fma_f32 v[116:117], v[116:117], 0.5, v[122:123] op_sel_hi:[1,0,1]
	v_pk_fma_f32 v[118:119], v[118:119], 0.5, v[120:121] op_sel_hi:[1,0,1]
	v_cvt_pk_bf16_f32 v116, v116, v117
	v_cvt_pk_bf16_f32 v117, v118, v119
	global_store_dwordx2 v[138:139], v[116:117], off offset:256
	v_lshlrev_b32_e32 v118, 16, v116
	v_and_b32_e32 v116, 0xffff0000, v116
	v_lshlrev_b32_e32 v119, 16, v117
	v_and_b32_e32 v117, 0xffff0000, v117
	v_mul_f32_e32 v116, v116, v116
	v_mul_f32_e32 v117, v117, v117
	v_fmac_f32_e32 v116, v118, v118
	v_fmac_f32_e32 v117, v119, v119
	v_add_f32_e32 v116, v116, v117
	v_add_f32_e32 v120, v124, v116
	v_mov_b32_e32 v116, v172
	v_mov_b32_e32 v117, v173
	v_lshlrev_b32_e32 v118, 16, v116
	v_and_b32_e32 v119, 0xffff0000, v116
	v_lshlrev_b32_e32 v116, 16, v117
	v_and_b32_e32 v117, 0xffff0000, v117
	v_pk_fma_f32 v[112:113], v[112:113], 0.5, v[118:119] op_sel_hi:[1,0,1]
	v_pk_fma_f32 v[114:115], v[114:115], 0.5, v[116:117] op_sel_hi:[1,0,1]
	v_cvt_pk_bf16_f32 v112, v112, v113
	v_cvt_pk_bf16_f32 v113, v114, v115
	global_store_dwordx2 v[138:139], v[112:113], off offset:288
	v_lshlrev_b32_e32 v114, 16, v112
	v_and_b32_e32 v112, 0xffff0000, v112
	v_lshlrev_b32_e32 v115, 16, v113
	v_and_b32_e32 v113, 0xffff0000, v113
	v_mul_f32_e32 v112, v112, v112
	v_mul_f32_e32 v113, v113, v113
	v_fmac_f32_e32 v112, v114, v114
	v_fmac_f32_e32 v113, v115, v115
	v_add_f32_e32 v112, v112, v113
	v_add_f32_e32 v112, v120, v112
	ds_bpermute_b32 v113, v144, v112
	s_waitcnt lgkmcnt(0)
	v_add_f32_e32 v112, v112, v113
	ds_bpermute_b32 v113, v145, v112
	s_and_saveexec_b64 s[34:35], s[38:39]
	s_cbranch_execz .LBB0_2311
	v_lshlrev_b64 v[114:115], 6, v[136:137]
	v_lshl_add_u64 v[114:115], s[20:21], 0, v[114:115]
	v_lshl_add_u64 v[114:115], s[30:31], 2, v[114:115]
	s_lshl_b32 s66, s53, 2
	v_lshl_add_u64 v[114:115], v[114:115], 0, s[66:67]
	s_waitcnt lgkmcnt(0)
	v_add_f32_e32 v112, v112, v113
	global_store_dword v[114:115], v112, off
.LBB0_2311:
	s_or_b64 exec, exec, s[34:35]
	v_or_b32_e32 v112, 16, v136
	s_waitcnt lgkmcnt(0)
	v_ashrrev_i32_e32 v113, 31, v112
	v_lshlrev_b64 v[114:115], 11, v[112:113]
	v_lshl_add_u64 v[114:115], s[18:19], 0, v[114:115]
	v_lshl_add_u64 v[114:115], v[134:135], 1, v[114:115]
	v_mov_b32_e32 v116, v174
	v_mov_b32_e32 v117, v175
	v_lshlrev_b32_e32 v118, 16, v116
	v_and_b32_e32 v119, 0xffff0000, v116
	v_lshlrev_b32_e32 v116, 16, v117
	v_and_b32_e32 v117, 0xffff0000, v117
	v_pk_fma_f32 v[108:109], v[108:109], 0.5, v[118:119] op_sel_hi:[1,0,1]
	v_pk_fma_f32 v[110:111], v[110:111], 0.5, v[116:117] op_sel_hi:[1,0,1]
	v_cvt_pk_bf16_f32 v108, v108, v109
	v_cvt_pk_bf16_f32 v109, v110, v111
	global_store_dwordx2 v[114:115], v[108:109], off
	v_lshlrev_b32_e32 v110, 16, v108
	v_and_b32_e32 v108, 0xffff0000, v108
	v_lshlrev_b32_e32 v111, 16, v109
	v_and_b32_e32 v109, 0xffff0000, v109
	v_mul_f32_e32 v108, v108, v108
	v_mul_f32_e32 v109, v109, v109
	v_fmac_f32_e32 v108, v110, v110
	v_fmac_f32_e32 v109, v111, v111
	v_add_f32_e32 v116, v108, v109
	v_mov_b32_e32 v108, v176
	v_mov_b32_e32 v109, v177
	v_lshlrev_b32_e32 v110, 16, v108
	v_and_b32_e32 v111, 0xffff0000, v108
	v_lshlrev_b32_e32 v108, 16, v109
	v_and_b32_e32 v109, 0xffff0000, v109
	v_pk_fma_f32 v[104:105], v[104:105], 0.5, v[110:111] op_sel_hi:[1,0,1]
	v_pk_fma_f32 v[106:107], v[106:107], 0.5, v[108:109] op_sel_hi:[1,0,1]
	v_cvt_pk_bf16_f32 v104, v104, v105
	v_cvt_pk_bf16_f32 v105, v106, v107
	global_store_dwordx2 v[114:115], v[104:105], off offset:32
	v_lshlrev_b32_e32 v106, 16, v104
	v_and_b32_e32 v104, 0xffff0000, v104
	v_lshlrev_b32_e32 v107, 16, v105
	v_and_b32_e32 v105, 0xffff0000, v105
	v_mul_f32_e32 v104, v104, v104
	v_mul_f32_e32 v105, v105, v105
	v_fmac_f32_e32 v104, v106, v106
	v_fmac_f32_e32 v105, v107, v107
	v_add_f32_e32 v104, v104, v105
	v_add_f32_e32 v108, v116, v104
	v_mov_b32_e32 v104, v178
	v_mov_b32_e32 v105, v179
	v_lshlrev_b32_e32 v106, 16, v104
	v_and_b32_e32 v107, 0xffff0000, v104
	v_lshlrev_b32_e32 v104, 16, v105
	v_and_b32_e32 v105, 0xffff0000, v105
	v_pk_fma_f32 v[100:101], v[100:101], 0.5, v[106:107] op_sel_hi:[1,0,1]
	v_pk_fma_f32 v[102:103], v[102:103], 0.5, v[104:105] op_sel_hi:[1,0,1]
	v_cvt_pk_bf16_f32 v100, v100, v101
	v_cvt_pk_bf16_f32 v101, v102, v103
	global_store_dwordx2 v[114:115], v[100:101], off offset:256
	v_lshlrev_b32_e32 v102, 16, v100
	v_and_b32_e32 v100, 0xffff0000, v100
	v_lshlrev_b32_e32 v103, 16, v101
	v_and_b32_e32 v101, 0xffff0000, v101
	v_mul_f32_e32 v100, v100, v100
	v_mul_f32_e32 v101, v101, v101
	v_fmac_f32_e32 v100, v102, v102
	v_fmac_f32_e32 v101, v103, v103
	v_add_f32_e32 v100, v100, v101
	v_add_f32_e32 v104, v108, v100
	v_mov_b32_e32 v100, v180
	v_mov_b32_e32 v101, v181
	v_lshlrev_b32_e32 v102, 16, v100
	v_and_b32_e32 v103, 0xffff0000, v100
	v_lshlrev_b32_e32 v100, 16, v101
	v_and_b32_e32 v101, 0xffff0000, v101
	v_pk_fma_f32 v[96:97], v[96:97], 0.5, v[102:103] op_sel_hi:[1,0,1]
	v_pk_fma_f32 v[98:99], v[98:99], 0.5, v[100:101] op_sel_hi:[1,0,1]
	v_cvt_pk_bf16_f32 v96, v96, v97
	v_cvt_pk_bf16_f32 v97, v98, v99
	global_store_dwordx2 v[114:115], v[96:97], off offset:288
	v_lshlrev_b32_e32 v98, 16, v96
	v_and_b32_e32 v96, 0xffff0000, v96
	v_lshlrev_b32_e32 v99, 16, v97
	v_and_b32_e32 v97, 0xffff0000, v97
	v_mul_f32_e32 v96, v96, v96
	v_mul_f32_e32 v97, v97, v97
	v_fmac_f32_e32 v96, v98, v98
	v_fmac_f32_e32 v97, v99, v99
	v_add_f32_e32 v96, v96, v97
	v_add_f32_e32 v96, v104, v96
	ds_bpermute_b32 v97, v144, v96
	s_waitcnt lgkmcnt(0)
	v_add_f32_e32 v96, v96, v97
	ds_bpermute_b32 v97, v145, v96
	s_and_saveexec_b64 s[34:35], s[38:39]
	s_cbranch_execz .LBB0_2313
	v_lshlrev_b64 v[98:99], 6, v[112:113]
	v_lshl_add_u64 v[98:99], s[20:21], 0, v[98:99]
	v_lshl_add_u64 v[98:99], s[30:31], 2, v[98:99]
	s_lshl_b32 s66, s53, 2
	v_lshl_add_u64 v[98:99], v[98:99], 0, s[66:67]
	s_waitcnt lgkmcnt(0)
	v_add_f32_e32 v96, v96, v97
	global_store_dword v[98:99], v96, off
.LBB0_2313:
	s_or_b64 exec, exec, s[34:35]
	v_or_b32_e32 v96, 32, v136
	s_waitcnt lgkmcnt(0)
	v_ashrrev_i32_e32 v97, 31, v96
	v_lshlrev_b64 v[98:99], 11, v[96:97]
	v_lshl_add_u64 v[98:99], s[18:19], 0, v[98:99]
	v_lshl_add_u64 v[98:99], v[134:135], 1, v[98:99]
	v_mov_b32_e32 v100, v182
	v_mov_b32_e32 v101, v183
	v_lshlrev_b32_e32 v102, 16, v100
	v_and_b32_e32 v103, 0xffff0000, v100
	v_lshlrev_b32_e32 v100, 16, v101
	v_and_b32_e32 v101, 0xffff0000, v101
	v_pk_fma_f32 v[92:93], v[92:93], 0.5, v[102:103] op_sel_hi:[1,0,1]
	v_pk_fma_f32 v[94:95], v[94:95], 0.5, v[100:101] op_sel_hi:[1,0,1]
	v_cvt_pk_bf16_f32 v92, v92, v93
	v_cvt_pk_bf16_f32 v93, v94, v95
	global_store_dwordx2 v[98:99], v[92:93], off
	v_lshlrev_b32_e32 v94, 16, v92
	v_and_b32_e32 v92, 0xffff0000, v92
	v_lshlrev_b32_e32 v95, 16, v93
	v_and_b32_e32 v93, 0xffff0000, v93
	v_mul_f32_e32 v92, v92, v92
	v_mul_f32_e32 v93, v93, v93
	v_fmac_f32_e32 v92, v94, v94
	v_fmac_f32_e32 v93, v95, v95
	v_add_f32_e32 v100, v92, v93
	v_mov_b32_e32 v92, v184
	v_mov_b32_e32 v93, v185
	v_lshlrev_b32_e32 v94, 16, v92
	v_and_b32_e32 v95, 0xffff0000, v92
	v_lshlrev_b32_e32 v92, 16, v93
	v_and_b32_e32 v93, 0xffff0000, v93
	v_pk_fma_f32 v[88:89], v[88:89], 0.5, v[94:95] op_sel_hi:[1,0,1]
	v_pk_fma_f32 v[90:91], v[90:91], 0.5, v[92:93] op_sel_hi:[1,0,1]
	v_cvt_pk_bf16_f32 v88, v88, v89
	v_cvt_pk_bf16_f32 v89, v90, v91
	global_store_dwordx2 v[98:99], v[88:89], off offset:32
	v_lshlrev_b32_e32 v90, 16, v88
	v_and_b32_e32 v88, 0xffff0000, v88
	v_lshlrev_b32_e32 v91, 16, v89
	v_and_b32_e32 v89, 0xffff0000, v89
	v_mul_f32_e32 v88, v88, v88
	v_mul_f32_e32 v89, v89, v89
	v_fmac_f32_e32 v88, v90, v90
	v_fmac_f32_e32 v89, v91, v91
	v_add_f32_e32 v88, v88, v89
	v_add_f32_e32 v92, v100, v88
	v_mov_b32_e32 v88, v186
	v_mov_b32_e32 v89, v187
	v_lshlrev_b32_e32 v90, 16, v88
	v_and_b32_e32 v91, 0xffff0000, v88
	v_lshlrev_b32_e32 v88, 16, v89
	v_and_b32_e32 v89, 0xffff0000, v89
	v_pk_fma_f32 v[84:85], v[84:85], 0.5, v[90:91] op_sel_hi:[1,0,1]
	v_pk_fma_f32 v[86:87], v[86:87], 0.5, v[88:89] op_sel_hi:[1,0,1]
	v_cvt_pk_bf16_f32 v84, v84, v85
	v_cvt_pk_bf16_f32 v85, v86, v87
	global_store_dwordx2 v[98:99], v[84:85], off offset:256
	v_lshlrev_b32_e32 v86, 16, v84
	v_and_b32_e32 v84, 0xffff0000, v84
	v_lshlrev_b32_e32 v87, 16, v85
	v_and_b32_e32 v85, 0xffff0000, v85
	v_mul_f32_e32 v84, v84, v84
	v_mul_f32_e32 v85, v85, v85
	v_fmac_f32_e32 v84, v86, v86
	v_fmac_f32_e32 v85, v87, v87
	v_add_f32_e32 v84, v84, v85
	v_add_f32_e32 v88, v92, v84
	v_mov_b32_e32 v84, v188
	v_mov_b32_e32 v85, v189
	v_lshlrev_b32_e32 v86, 16, v84
	v_and_b32_e32 v87, 0xffff0000, v84
	v_lshlrev_b32_e32 v84, 16, v85
	v_and_b32_e32 v85, 0xffff0000, v85
	v_pk_fma_f32 v[80:81], v[80:81], 0.5, v[86:87] op_sel_hi:[1,0,1]
	v_pk_fma_f32 v[82:83], v[82:83], 0.5, v[84:85] op_sel_hi:[1,0,1]
	v_cvt_pk_bf16_f32 v80, v80, v81
	v_cvt_pk_bf16_f32 v81, v82, v83
	global_store_dwordx2 v[98:99], v[80:81], off offset:288
	v_lshlrev_b32_e32 v82, 16, v80
	v_and_b32_e32 v80, 0xffff0000, v80
	v_lshlrev_b32_e32 v83, 16, v81
	v_and_b32_e32 v81, 0xffff0000, v81
	v_mul_f32_e32 v80, v80, v80
	v_mul_f32_e32 v81, v81, v81
	v_fmac_f32_e32 v80, v82, v82
	v_fmac_f32_e32 v81, v83, v83
	v_add_f32_e32 v80, v80, v81
	v_add_f32_e32 v80, v88, v80
	ds_bpermute_b32 v81, v144, v80
	s_waitcnt lgkmcnt(0)
	v_add_f32_e32 v80, v80, v81
	ds_bpermute_b32 v81, v145, v80
	s_and_saveexec_b64 s[34:35], s[38:39]
	s_cbranch_execz .LBB0_2315
	v_lshlrev_b64 v[82:83], 6, v[96:97]
	v_lshl_add_u64 v[82:83], s[20:21], 0, v[82:83]
	v_lshl_add_u64 v[82:83], s[30:31], 2, v[82:83]
	s_lshl_b32 s66, s53, 2
	v_lshl_add_u64 v[82:83], v[82:83], 0, s[66:67]
	s_waitcnt lgkmcnt(0)
	v_add_f32_e32 v80, v80, v81
	global_store_dword v[82:83], v80, off
.LBB0_2315:
	s_or_b64 exec, exec, s[34:35]
	v_or_b32_e32 v80, 48, v136
	s_waitcnt lgkmcnt(0)
	v_ashrrev_i32_e32 v81, 31, v80
	v_lshlrev_b64 v[82:83], 11, v[80:81]
	v_lshl_add_u64 v[82:83], s[18:19], 0, v[82:83]
	v_lshl_add_u64 v[82:83], v[134:135], 1, v[82:83]
	v_mov_b32_e32 v84, v190
	v_mov_b32_e32 v85, v191
	v_lshlrev_b32_e32 v86, 16, v84
	v_and_b32_e32 v87, 0xffff0000, v84
	v_lshlrev_b32_e32 v84, 16, v85
	v_and_b32_e32 v85, 0xffff0000, v85
	v_pk_fma_f32 v[76:77], v[76:77], 0.5, v[86:87] op_sel_hi:[1,0,1]
	v_pk_fma_f32 v[78:79], v[78:79], 0.5, v[84:85] op_sel_hi:[1,0,1]
	v_cvt_pk_bf16_f32 v76, v76, v77
	v_cvt_pk_bf16_f32 v77, v78, v79
	global_store_dwordx2 v[82:83], v[76:77], off
	v_lshlrev_b32_e32 v78, 16, v76
	v_and_b32_e32 v76, 0xffff0000, v76
	v_lshlrev_b32_e32 v79, 16, v77
	v_and_b32_e32 v77, 0xffff0000, v77
	v_mul_f32_e32 v76, v76, v76
	v_mul_f32_e32 v77, v77, v77
	v_fmac_f32_e32 v76, v78, v78
	v_fmac_f32_e32 v77, v79, v79
	v_add_f32_e32 v84, v76, v77
	v_mov_b32_e32 v76, v192
	v_mov_b32_e32 v77, v193
	v_lshlrev_b32_e32 v78, 16, v76
	v_and_b32_e32 v79, 0xffff0000, v76
	v_lshlrev_b32_e32 v76, 16, v77
	v_and_b32_e32 v77, 0xffff0000, v77
	v_pk_fma_f32 v[72:73], v[72:73], 0.5, v[78:79] op_sel_hi:[1,0,1]
	v_pk_fma_f32 v[74:75], v[74:75], 0.5, v[76:77] op_sel_hi:[1,0,1]
	v_cvt_pk_bf16_f32 v72, v72, v73
	v_cvt_pk_bf16_f32 v73, v74, v75
	global_store_dwordx2 v[82:83], v[72:73], off offset:32
	v_lshlrev_b32_e32 v74, 16, v72
	v_and_b32_e32 v72, 0xffff0000, v72
	v_lshlrev_b32_e32 v75, 16, v73
	v_and_b32_e32 v73, 0xffff0000, v73
	v_mul_f32_e32 v72, v72, v72
	v_mul_f32_e32 v73, v73, v73
	v_fmac_f32_e32 v72, v74, v74
	v_fmac_f32_e32 v73, v75, v75
	v_add_f32_e32 v72, v72, v73
	v_add_f32_e32 v76, v84, v72
	v_mov_b32_e32 v72, v194
	v_mov_b32_e32 v73, v195
	v_lshlrev_b32_e32 v74, 16, v72
	v_and_b32_e32 v75, 0xffff0000, v72
	v_lshlrev_b32_e32 v72, 16, v73
	v_and_b32_e32 v73, 0xffff0000, v73
	v_pk_fma_f32 v[68:69], v[68:69], 0.5, v[74:75] op_sel_hi:[1,0,1]
	v_pk_fma_f32 v[70:71], v[70:71], 0.5, v[72:73] op_sel_hi:[1,0,1]
	v_cvt_pk_bf16_f32 v68, v68, v69
	v_cvt_pk_bf16_f32 v69, v70, v71
	global_store_dwordx2 v[82:83], v[68:69], off offset:256
	v_lshlrev_b32_e32 v70, 16, v68
	v_and_b32_e32 v68, 0xffff0000, v68
	v_lshlrev_b32_e32 v71, 16, v69
	v_and_b32_e32 v69, 0xffff0000, v69
	v_mul_f32_e32 v68, v68, v68
	v_mul_f32_e32 v69, v69, v69
	v_fmac_f32_e32 v68, v70, v70
	v_fmac_f32_e32 v69, v71, v71
	v_add_f32_e32 v68, v68, v69
	v_add_f32_e32 v72, v76, v68
	v_mov_b32_e32 v68, v196
	v_mov_b32_e32 v69, v197
	v_lshlrev_b32_e32 v70, 16, v68
	v_and_b32_e32 v71, 0xffff0000, v68
	v_lshlrev_b32_e32 v68, 16, v69
	v_and_b32_e32 v69, 0xffff0000, v69
	v_pk_fma_f32 v[64:65], v[64:65], 0.5, v[70:71] op_sel_hi:[1,0,1]
	v_pk_fma_f32 v[66:67], v[66:67], 0.5, v[68:69] op_sel_hi:[1,0,1]
	v_cvt_pk_bf16_f32 v64, v64, v65
	v_cvt_pk_bf16_f32 v65, v66, v67
	global_store_dwordx2 v[82:83], v[64:65], off offset:288
	v_lshlrev_b32_e32 v66, 16, v64
	v_and_b32_e32 v64, 0xffff0000, v64
	v_lshlrev_b32_e32 v67, 16, v65
	v_and_b32_e32 v65, 0xffff0000, v65
	v_mul_f32_e32 v64, v64, v64
	v_mul_f32_e32 v65, v65, v65
	v_fmac_f32_e32 v64, v66, v66
	v_fmac_f32_e32 v65, v67, v67
	v_add_f32_e32 v64, v64, v65
	v_add_f32_e32 v64, v72, v64
	ds_bpermute_b32 v65, v144, v64
	s_waitcnt lgkmcnt(0)
	v_add_f32_e32 v64, v64, v65
	ds_bpermute_b32 v65, v145, v64
	s_and_saveexec_b64 s[34:35], s[38:39]
	s_cbranch_execz .LBB0_2317
	v_lshlrev_b64 v[66:67], 6, v[80:81]
	v_lshl_add_u64 v[66:67], s[20:21], 0, v[66:67]
	v_lshl_add_u64 v[66:67], s[30:31], 2, v[66:67]
	s_lshl_b32 s66, s53, 2
	v_lshl_add_u64 v[66:67], v[66:67], 0, s[66:67]
	s_waitcnt lgkmcnt(0)
	v_add_f32_e32 v64, v64, v65
	global_store_dword v[66:67], v64, off
.LBB0_2317:
	s_or_b64 exec, exec, s[34:35]
	v_add_u32_e32 v64, 0x80, v136
	s_waitcnt lgkmcnt(0)
	v_ashrrev_i32_e32 v65, 31, v64
	v_lshlrev_b64 v[66:67], 11, v[64:65]
	v_lshl_add_u64 v[66:67], s[18:19], 0, v[66:67]
	v_lshl_add_u64 v[66:67], v[134:135], 1, v[66:67]
	v_mov_b32_e32 v68, v198
	v_mov_b32_e32 v69, v199
	v_lshlrev_b32_e32 v70, 16, v68
	v_and_b32_e32 v71, 0xffff0000, v68
	v_lshlrev_b32_e32 v68, 16, v69
	v_and_b32_e32 v69, 0xffff0000, v69
	v_pk_fma_f32 v[60:61], v[60:61], 0.5, v[70:71] op_sel_hi:[1,0,1]
	v_pk_fma_f32 v[62:63], v[62:63], 0.5, v[68:69] op_sel_hi:[1,0,1]
	v_cvt_pk_bf16_f32 v60, v60, v61
	v_cvt_pk_bf16_f32 v61, v62, v63
	global_store_dwordx2 v[66:67], v[60:61], off
	v_lshlrev_b32_e32 v62, 16, v60
	v_and_b32_e32 v60, 0xffff0000, v60
	v_lshlrev_b32_e32 v63, 16, v61
	v_and_b32_e32 v61, 0xffff0000, v61
	v_mul_f32_e32 v60, v60, v60
	v_mul_f32_e32 v61, v61, v61
	v_fmac_f32_e32 v60, v62, v62
	v_fmac_f32_e32 v61, v63, v63
	v_add_f32_e32 v68, v60, v61
	v_mov_b32_e32 v60, v200
	v_mov_b32_e32 v61, v201
	v_lshlrev_b32_e32 v62, 16, v60
	v_and_b32_e32 v63, 0xffff0000, v60
	v_lshlrev_b32_e32 v60, 16, v61
	v_and_b32_e32 v61, 0xffff0000, v61
	v_pk_fma_f32 v[56:57], v[56:57], 0.5, v[62:63] op_sel_hi:[1,0,1]
	v_pk_fma_f32 v[58:59], v[58:59], 0.5, v[60:61] op_sel_hi:[1,0,1]
	v_cvt_pk_bf16_f32 v56, v56, v57
	v_cvt_pk_bf16_f32 v57, v58, v59
	global_store_dwordx2 v[66:67], v[56:57], off offset:32
	v_lshlrev_b32_e32 v58, 16, v56
	v_and_b32_e32 v56, 0xffff0000, v56
	v_lshlrev_b32_e32 v59, 16, v57
	v_and_b32_e32 v57, 0xffff0000, v57
	v_mul_f32_e32 v56, v56, v56
	v_mul_f32_e32 v57, v57, v57
	v_fmac_f32_e32 v56, v58, v58
	v_fmac_f32_e32 v57, v59, v59
	v_add_f32_e32 v56, v56, v57
	v_add_f32_e32 v60, v68, v56
	v_mov_b32_e32 v56, v202
	v_mov_b32_e32 v57, v203
	v_lshlrev_b32_e32 v58, 16, v56
	v_and_b32_e32 v59, 0xffff0000, v56
	v_lshlrev_b32_e32 v56, 16, v57
	v_and_b32_e32 v57, 0xffff0000, v57
	v_pk_fma_f32 v[52:53], v[52:53], 0.5, v[58:59] op_sel_hi:[1,0,1]
	v_pk_fma_f32 v[54:55], v[54:55], 0.5, v[56:57] op_sel_hi:[1,0,1]
	v_cvt_pk_bf16_f32 v52, v52, v53
	v_cvt_pk_bf16_f32 v53, v54, v55
	global_store_dwordx2 v[66:67], v[52:53], off offset:256
	v_lshlrev_b32_e32 v54, 16, v52
	v_and_b32_e32 v52, 0xffff0000, v52
	v_lshlrev_b32_e32 v55, 16, v53
	v_and_b32_e32 v53, 0xffff0000, v53
	v_mul_f32_e32 v52, v52, v52
	v_mul_f32_e32 v53, v53, v53
	v_fmac_f32_e32 v52, v54, v54
	v_fmac_f32_e32 v53, v55, v55
	v_add_f32_e32 v52, v52, v53
	v_add_f32_e32 v56, v60, v52
	v_mov_b32_e32 v52, v204
	v_mov_b32_e32 v53, v205
	v_lshlrev_b32_e32 v54, 16, v52
	v_and_b32_e32 v55, 0xffff0000, v52
	v_lshlrev_b32_e32 v52, 16, v53
	v_and_b32_e32 v53, 0xffff0000, v53
	v_pk_fma_f32 v[48:49], v[48:49], 0.5, v[54:55] op_sel_hi:[1,0,1]
	v_pk_fma_f32 v[50:51], v[50:51], 0.5, v[52:53] op_sel_hi:[1,0,1]
	v_cvt_pk_bf16_f32 v48, v48, v49
	v_cvt_pk_bf16_f32 v49, v50, v51
	global_store_dwordx2 v[66:67], v[48:49], off offset:288
	v_lshlrev_b32_e32 v50, 16, v48
	v_and_b32_e32 v48, 0xffff0000, v48
	v_lshlrev_b32_e32 v51, 16, v49
	v_and_b32_e32 v49, 0xffff0000, v49
	v_mul_f32_e32 v48, v48, v48
	v_mul_f32_e32 v49, v49, v49
	v_fmac_f32_e32 v48, v50, v50
	v_fmac_f32_e32 v49, v51, v51
	v_add_f32_e32 v48, v48, v49
	v_add_f32_e32 v48, v56, v48
	ds_bpermute_b32 v49, v144, v48
	s_waitcnt lgkmcnt(0)
	v_add_f32_e32 v48, v48, v49
	ds_bpermute_b32 v49, v145, v48
	s_and_saveexec_b64 s[34:35], s[38:39]
	s_cbranch_execz .LBB0_2319
	v_lshlrev_b64 v[50:51], 6, v[64:65]
	v_lshl_add_u64 v[50:51], s[20:21], 0, v[50:51]
	v_lshl_add_u64 v[50:51], s[30:31], 2, v[50:51]
	s_lshl_b32 s66, s53, 2
	v_lshl_add_u64 v[50:51], v[50:51], 0, s[66:67]
	s_waitcnt lgkmcnt(0)
	v_add_f32_e32 v48, v48, v49
	global_store_dword v[50:51], v48, off
.LBB0_2319:
	s_or_b64 exec, exec, s[34:35]
	v_add_u32_e32 v48, 0x90, v136
	s_waitcnt lgkmcnt(0)
	v_ashrrev_i32_e32 v49, 31, v48
	v_lshlrev_b64 v[50:51], 11, v[48:49]
	v_lshl_add_u64 v[50:51], s[18:19], 0, v[50:51]
	v_lshl_add_u64 v[50:51], v[134:135], 1, v[50:51]
	v_mov_b32_e32 v52, v206
	v_mov_b32_e32 v53, v207
	v_lshlrev_b32_e32 v54, 16, v52
	v_and_b32_e32 v55, 0xffff0000, v52
	v_lshlrev_b32_e32 v52, 16, v53
	v_and_b32_e32 v53, 0xffff0000, v53
	v_pk_fma_f32 v[44:45], v[44:45], 0.5, v[54:55] op_sel_hi:[1,0,1]
	v_pk_fma_f32 v[46:47], v[46:47], 0.5, v[52:53] op_sel_hi:[1,0,1]
	v_cvt_pk_bf16_f32 v44, v44, v45
	v_cvt_pk_bf16_f32 v45, v46, v47
	global_store_dwordx2 v[50:51], v[44:45], off
	v_lshlrev_b32_e32 v46, 16, v44
	v_and_b32_e32 v44, 0xffff0000, v44
	v_lshlrev_b32_e32 v47, 16, v45
	v_and_b32_e32 v45, 0xffff0000, v45
	v_mul_f32_e32 v44, v44, v44
	v_mul_f32_e32 v45, v45, v45
	v_fmac_f32_e32 v44, v46, v46
	v_fmac_f32_e32 v45, v47, v47
	v_add_f32_e32 v52, v44, v45
	v_mov_b32_e32 v44, v222
	v_mov_b32_e32 v45, v223
	v_lshlrev_b32_e32 v46, 16, v44
	v_and_b32_e32 v47, 0xffff0000, v44
	v_lshlrev_b32_e32 v44, 16, v45
	v_and_b32_e32 v45, 0xffff0000, v45
	v_pk_fma_f32 v[40:41], v[40:41], 0.5, v[46:47] op_sel_hi:[1,0,1]
	v_pk_fma_f32 v[42:43], v[42:43], 0.5, v[44:45] op_sel_hi:[1,0,1]
	v_cvt_pk_bf16_f32 v40, v40, v41
	v_cvt_pk_bf16_f32 v41, v42, v43
	global_store_dwordx2 v[50:51], v[40:41], off offset:32
	v_lshlrev_b32_e32 v42, 16, v40
	v_and_b32_e32 v40, 0xffff0000, v40
	v_lshlrev_b32_e32 v43, 16, v41
	v_and_b32_e32 v41, 0xffff0000, v41
	v_mul_f32_e32 v40, v40, v40
	v_mul_f32_e32 v41, v41, v41
	v_fmac_f32_e32 v40, v42, v42
	v_fmac_f32_e32 v41, v43, v43
	v_add_f32_e32 v40, v40, v41
	v_add_f32_e32 v44, v52, v40
	v_mov_b32_e32 v40, v224
	v_mov_b32_e32 v41, v225
	v_lshlrev_b32_e32 v42, 16, v40
	v_and_b32_e32 v43, 0xffff0000, v40
	v_lshlrev_b32_e32 v40, 16, v41
	v_and_b32_e32 v41, 0xffff0000, v41
	v_pk_fma_f32 v[36:37], v[36:37], 0.5, v[42:43] op_sel_hi:[1,0,1]
	v_pk_fma_f32 v[38:39], v[38:39], 0.5, v[40:41] op_sel_hi:[1,0,1]
	v_cvt_pk_bf16_f32 v36, v36, v37
	v_cvt_pk_bf16_f32 v37, v38, v39
	global_store_dwordx2 v[50:51], v[36:37], off offset:256
	v_lshlrev_b32_e32 v38, 16, v36
	v_and_b32_e32 v36, 0xffff0000, v36
	v_lshlrev_b32_e32 v39, 16, v37
	v_and_b32_e32 v37, 0xffff0000, v37
	v_mul_f32_e32 v36, v36, v36
	v_mul_f32_e32 v37, v37, v37
	v_fmac_f32_e32 v36, v38, v38
	v_fmac_f32_e32 v37, v39, v39
	v_add_f32_e32 v36, v36, v37
	v_add_f32_e32 v40, v44, v36
	v_mov_b32_e32 v36, v226
	v_mov_b32_e32 v37, v227
	v_lshlrev_b32_e32 v38, 16, v36
	v_and_b32_e32 v39, 0xffff0000, v36
	v_lshlrev_b32_e32 v36, 16, v37
	v_and_b32_e32 v37, 0xffff0000, v37
	v_pk_fma_f32 v[32:33], v[32:33], 0.5, v[38:39] op_sel_hi:[1,0,1]
	v_pk_fma_f32 v[34:35], v[34:35], 0.5, v[36:37] op_sel_hi:[1,0,1]
	v_cvt_pk_bf16_f32 v32, v32, v33
	v_cvt_pk_bf16_f32 v33, v34, v35
	global_store_dwordx2 v[50:51], v[32:33], off offset:288
	v_lshlrev_b32_e32 v34, 16, v32
	v_and_b32_e32 v32, 0xffff0000, v32
	v_lshlrev_b32_e32 v35, 16, v33
	v_and_b32_e32 v33, 0xffff0000, v33
	v_mul_f32_e32 v32, v32, v32
	v_mul_f32_e32 v33, v33, v33
	v_fmac_f32_e32 v32, v34, v34
	v_fmac_f32_e32 v33, v35, v35
	v_add_f32_e32 v32, v32, v33
	v_add_f32_e32 v32, v40, v32
	ds_bpermute_b32 v33, v144, v32
	s_waitcnt lgkmcnt(0)
	v_add_f32_e32 v32, v32, v33
	ds_bpermute_b32 v33, v145, v32
	s_and_saveexec_b64 s[34:35], s[38:39]
	s_cbranch_execz .LBB0_2321
	v_lshlrev_b64 v[34:35], 6, v[48:49]
	v_lshl_add_u64 v[34:35], s[20:21], 0, v[34:35]
	v_lshl_add_u64 v[34:35], s[30:31], 2, v[34:35]
	s_lshl_b32 s66, s53, 2
	v_lshl_add_u64 v[34:35], v[34:35], 0, s[66:67]
	s_waitcnt lgkmcnt(0)
	v_add_f32_e32 v32, v32, v33
	global_store_dword v[34:35], v32, off
.LBB0_2321:
	s_or_b64 exec, exec, s[34:35]
	v_add_u32_e32 v32, 0xa0, v136
	s_waitcnt lgkmcnt(0)
	v_ashrrev_i32_e32 v33, 31, v32
	v_lshlrev_b64 v[34:35], 11, v[32:33]
	v_lshl_add_u64 v[34:35], s[18:19], 0, v[34:35]
	v_lshl_add_u64 v[34:35], v[134:135], 1, v[34:35]
	v_mov_b32_e32 v36, v228
	v_mov_b32_e32 v37, v229
	v_lshlrev_b32_e32 v38, 16, v36
	v_and_b32_e32 v39, 0xffff0000, v36
	v_lshlrev_b32_e32 v36, 16, v37
	v_and_b32_e32 v37, 0xffff0000, v37
	v_pk_fma_f32 v[28:29], v[28:29], 0.5, v[38:39] op_sel_hi:[1,0,1]
	v_pk_fma_f32 v[30:31], v[30:31], 0.5, v[36:37] op_sel_hi:[1,0,1]
	v_cvt_pk_bf16_f32 v28, v28, v29
	v_cvt_pk_bf16_f32 v29, v30, v31
	global_store_dwordx2 v[34:35], v[28:29], off
	v_lshlrev_b32_e32 v30, 16, v28
	v_and_b32_e32 v28, 0xffff0000, v28
	v_lshlrev_b32_e32 v31, 16, v29
	v_and_b32_e32 v29, 0xffff0000, v29
	v_mul_f32_e32 v28, v28, v28
	v_mul_f32_e32 v29, v29, v29
	v_fmac_f32_e32 v28, v30, v30
	v_fmac_f32_e32 v29, v31, v31
	v_add_f32_e32 v36, v28, v29
	v_mov_b32_e32 v28, v230
	v_mov_b32_e32 v29, v231
	v_lshlrev_b32_e32 v30, 16, v28
	v_and_b32_e32 v31, 0xffff0000, v28
	v_lshlrev_b32_e32 v28, 16, v29
	v_and_b32_e32 v29, 0xffff0000, v29
	v_pk_fma_f32 v[24:25], v[24:25], 0.5, v[30:31] op_sel_hi:[1,0,1]
	v_pk_fma_f32 v[26:27], v[26:27], 0.5, v[28:29] op_sel_hi:[1,0,1]
	v_cvt_pk_bf16_f32 v24, v24, v25
	v_cvt_pk_bf16_f32 v25, v26, v27
	global_store_dwordx2 v[34:35], v[24:25], off offset:32
	v_lshlrev_b32_e32 v26, 16, v24
	v_and_b32_e32 v24, 0xffff0000, v24
	v_lshlrev_b32_e32 v27, 16, v25
	v_and_b32_e32 v25, 0xffff0000, v25
	v_mul_f32_e32 v24, v24, v24
	v_mul_f32_e32 v25, v25, v25
	v_fmac_f32_e32 v24, v26, v26
	v_fmac_f32_e32 v25, v27, v27
	v_add_f32_e32 v24, v24, v25
	v_add_f32_e32 v28, v36, v24
	v_mov_b32_e32 v24, v232
	v_mov_b32_e32 v25, v233
	v_lshlrev_b32_e32 v26, 16, v24
	v_and_b32_e32 v27, 0xffff0000, v24
	v_lshlrev_b32_e32 v24, 16, v25
	v_and_b32_e32 v25, 0xffff0000, v25
	v_pk_fma_f32 v[20:21], v[20:21], 0.5, v[26:27] op_sel_hi:[1,0,1]
	v_pk_fma_f32 v[22:23], v[22:23], 0.5, v[24:25] op_sel_hi:[1,0,1]
	v_cvt_pk_bf16_f32 v20, v20, v21
	v_cvt_pk_bf16_f32 v21, v22, v23
	global_store_dwordx2 v[34:35], v[20:21], off offset:256
	v_lshlrev_b32_e32 v22, 16, v20
	v_and_b32_e32 v20, 0xffff0000, v20
	v_lshlrev_b32_e32 v23, 16, v21
	v_and_b32_e32 v21, 0xffff0000, v21
	v_mul_f32_e32 v20, v20, v20
	v_mul_f32_e32 v21, v21, v21
	v_fmac_f32_e32 v20, v22, v22
	v_fmac_f32_e32 v21, v23, v23
	v_add_f32_e32 v20, v20, v21
	v_add_f32_e32 v24, v28, v20
	v_mov_b32_e32 v20, v234
	v_mov_b32_e32 v21, v235
	v_lshlrev_b32_e32 v22, 16, v20
	v_and_b32_e32 v23, 0xffff0000, v20
	v_lshlrev_b32_e32 v20, 16, v21
	v_and_b32_e32 v21, 0xffff0000, v21
	v_pk_fma_f32 v[16:17], v[16:17], 0.5, v[22:23] op_sel_hi:[1,0,1]
	v_pk_fma_f32 v[18:19], v[18:19], 0.5, v[20:21] op_sel_hi:[1,0,1]
	v_cvt_pk_bf16_f32 v16, v16, v17
	v_cvt_pk_bf16_f32 v17, v18, v19
	global_store_dwordx2 v[34:35], v[16:17], off offset:288
	v_lshlrev_b32_e32 v18, 16, v16
	v_and_b32_e32 v16, 0xffff0000, v16
	v_lshlrev_b32_e32 v19, 16, v17
	v_and_b32_e32 v17, 0xffff0000, v17
	v_mul_f32_e32 v16, v16, v16
	v_mul_f32_e32 v17, v17, v17
	v_fmac_f32_e32 v16, v18, v18
	v_fmac_f32_e32 v17, v19, v19
	v_add_f32_e32 v16, v16, v17
	v_add_f32_e32 v16, v24, v16
	ds_bpermute_b32 v17, v144, v16
	s_waitcnt lgkmcnt(0)
	v_add_f32_e32 v16, v16, v17
	ds_bpermute_b32 v17, v145, v16
	s_and_saveexec_b64 s[34:35], s[38:39]
	s_cbranch_execz .LBB0_2323
	v_lshlrev_b64 v[18:19], 6, v[32:33]
	v_lshl_add_u64 v[18:19], s[20:21], 0, v[18:19]
	v_lshl_add_u64 v[18:19], s[30:31], 2, v[18:19]
	s_lshl_b32 s66, s53, 2
	v_lshl_add_u64 v[18:19], v[18:19], 0, s[66:67]
	s_waitcnt lgkmcnt(0)
	v_add_f32_e32 v16, v16, v17
	global_store_dword v[18:19], v16, off
.LBB0_2323:
	s_or_b64 exec, exec, s[34:35]
	v_add_u32_e32 v16, 0xb0, v136
	s_waitcnt lgkmcnt(0)
	v_ashrrev_i32_e32 v17, 31, v16
	v_lshlrev_b64 v[18:19], 11, v[16:17]
	v_lshl_add_u64 v[18:19], s[18:19], 0, v[18:19]
	v_lshl_add_u64 v[18:19], v[134:135], 1, v[18:19]
	v_mov_b32_e32 v20, v236
	v_mov_b32_e32 v21, v237
	v_lshlrev_b32_e32 v22, 16, v20
	v_and_b32_e32 v23, 0xffff0000, v20
	v_lshlrev_b32_e32 v20, 16, v21
	v_and_b32_e32 v21, 0xffff0000, v21
	v_pk_fma_f32 v[12:13], v[12:13], 0.5, v[22:23] op_sel_hi:[1,0,1]
	v_pk_fma_f32 v[14:15], v[14:15], 0.5, v[20:21] op_sel_hi:[1,0,1]
	v_cvt_pk_bf16_f32 v12, v12, v13
	v_cvt_pk_bf16_f32 v13, v14, v15
	global_store_dwordx2 v[18:19], v[12:13], off
	v_lshlrev_b32_e32 v14, 16, v12
	v_and_b32_e32 v12, 0xffff0000, v12
	v_lshlrev_b32_e32 v15, 16, v13
	v_and_b32_e32 v13, 0xffff0000, v13
	v_mul_f32_e32 v12, v12, v12
	v_mul_f32_e32 v13, v13, v13
	v_fmac_f32_e32 v12, v14, v14
	v_fmac_f32_e32 v13, v15, v15
	v_add_f32_e32 v20, v12, v13
	v_mov_b32_e32 v12, v238
	v_mov_b32_e32 v13, v239
	v_lshlrev_b32_e32 v14, 16, v12
	v_and_b32_e32 v15, 0xffff0000, v12
	v_lshlrev_b32_e32 v12, 16, v13
	v_and_b32_e32 v13, 0xffff0000, v13
	v_pk_fma_f32 v[8:9], v[8:9], 0.5, v[14:15] op_sel_hi:[1,0,1]
	v_pk_fma_f32 v[10:11], v[10:11], 0.5, v[12:13] op_sel_hi:[1,0,1]
	v_cvt_pk_bf16_f32 v8, v8, v9
	v_cvt_pk_bf16_f32 v9, v10, v11
	global_store_dwordx2 v[18:19], v[8:9], off offset:32
	v_lshlrev_b32_e32 v10, 16, v8
	v_and_b32_e32 v8, 0xffff0000, v8
	v_lshlrev_b32_e32 v11, 16, v9
	v_and_b32_e32 v9, 0xffff0000, v9
	v_mul_f32_e32 v8, v8, v8
	v_mul_f32_e32 v9, v9, v9
	v_fmac_f32_e32 v8, v10, v10
	v_fmac_f32_e32 v9, v11, v11
	v_add_f32_e32 v8, v8, v9
	v_add_f32_e32 v12, v20, v8
	v_mov_b32_e32 v8, v240
	v_mov_b32_e32 v9, v241
	v_lshlrev_b32_e32 v10, 16, v8
	v_and_b32_e32 v11, 0xffff0000, v8
	v_lshlrev_b32_e32 v8, 16, v9
	v_and_b32_e32 v9, 0xffff0000, v9
	v_pk_fma_f32 v[4:5], v[4:5], 0.5, v[10:11] op_sel_hi:[1,0,1]
	v_pk_fma_f32 v[6:7], v[6:7], 0.5, v[8:9] op_sel_hi:[1,0,1]
	v_cvt_pk_bf16_f32 v4, v4, v5
	v_cvt_pk_bf16_f32 v5, v6, v7
	global_store_dwordx2 v[18:19], v[4:5], off offset:256
	v_lshlrev_b32_e32 v6, 16, v4
	v_and_b32_e32 v4, 0xffff0000, v4
	v_lshlrev_b32_e32 v7, 16, v5
	v_and_b32_e32 v5, 0xffff0000, v5
	v_mul_f32_e32 v4, v4, v4
	v_mul_f32_e32 v5, v5, v5
	v_fmac_f32_e32 v4, v6, v6
	v_fmac_f32_e32 v5, v7, v7
	v_add_f32_e32 v4, v4, v5
	v_add_f32_e32 v8, v12, v4
	v_mov_b32_e32 v4, v242
	v_mov_b32_e32 v5, v243
	v_lshlrev_b32_e32 v6, 16, v4
	v_and_b32_e32 v7, 0xffff0000, v4
	v_lshlrev_b32_e32 v4, 16, v5
	v_and_b32_e32 v5, 0xffff0000, v5
	v_pk_fma_f32 v[0:1], v[0:1], 0.5, v[6:7] op_sel_hi:[1,0,1]
	v_pk_fma_f32 v[2:3], v[2:3], 0.5, v[4:5] op_sel_hi:[1,0,1]
	v_cvt_pk_bf16_f32 v0, v0, v1
	v_cvt_pk_bf16_f32 v1, v2, v3
	global_store_dwordx2 v[18:19], v[0:1], off offset:288
	v_lshlrev_b32_e32 v2, 16, v0
	v_and_b32_e32 v0, 0xffff0000, v0
	v_lshlrev_b32_e32 v3, 16, v1
	v_and_b32_e32 v1, 0xffff0000, v1
	v_mul_f32_e32 v0, v0, v0
	v_mul_f32_e32 v1, v1, v1
	v_fmac_f32_e32 v0, v2, v2
	v_fmac_f32_e32 v1, v3, v3
	v_add_f32_e32 v0, v0, v1
	v_add_f32_e32 v0, v8, v0
	ds_bpermute_b32 v1, v144, v0
	s_waitcnt lgkmcnt(0)
	v_add_f32_e32 v0, v0, v1
	ds_bpermute_b32 v1, v145, v0
	s_and_saveexec_b64 s[34:35], s[38:39]
	s_cbranch_execz .LBB0_2325
	v_lshlrev_b64 v[2:3], 6, v[16:17]
	v_lshl_add_u64 v[2:3], s[20:21], 0, v[2:3]
	v_lshl_add_u64 v[2:3], s[30:31], 2, v[2:3]
	s_lshl_b32 s66, s53, 2
	v_lshl_add_u64 v[2:3], v[2:3], 0, s[66:67]
	s_waitcnt lgkmcnt(0)
	v_add_f32_e32 v0, v0, v1
	global_store_dword v[2:3], v0, off
